# GEMM K-loops: setprio before pre-MFMA barrier, drop redundant lgkmcnt wait, drop mid-block setprio pair, barrier before setprio 0
# speedup vs baseline: 1.0069x; 1.0069x over previous
.LBB0_205:
	s_add_u32 s16, s42, 0xfff80080
	s_addc_u32 s17, s43, -1
	s_add_i32 s89, 0, 0x10000
	s_cmp_eq_u32 s88, 28
	s_cselect_b32 s45, s27, s17
	s_cselect_b32 s44, s73, s16
	s_cselect_b32 s29, s23, s78
	s_cselect_b32 s28, s74, s77
	s_add_i32 s91, 0, 0x14000
	v_add_u32_e32 v144, s89, v227
	v_add_u32_e32 v170, s91, v227
	ds_read_b128 v[132:135], v144
	ds_read_b128 v[136:139], v144 offset:1024
	ds_read_b128 v[140:143], v144 offset:2048
	ds_read_b128 v[144:147], v144 offset:3072
	ds_read_b128 v[148:151], v170
	ds_read_b128 v[152:155], v170 offset:1024
	ds_read_b128 v[166:169], v170 offset:2048
	ds_read_b128 v[170:173], v170 offset:3072
	v_lshl_add_u64 v[216:217], s[42:43], 0, v[162:163]
	s_add_i32 m0, s31, 0xc000
	ds_read_b128 v[184:187], v229
	ds_read_b128 v[188:191], v229 offset:1024
	ds_read_b128 v[192:195], v229 offset:2048
	ds_read_b128 v[196:199], v229 offset:3072
	ds_read_b128 v[200:203], v229 offset:4096
	ds_read_b128 v[204:207], v229 offset:5120
	ds_read_b128 v[208:211], v229 offset:6144
	ds_read_b128 v[212:215], v229 offset:7168
	global_load_lds_dwordx4 v[216:217], off
	v_lshl_add_u64 v[216:217], s[42:43], 0, v[164:165]
	s_add_i32 m0, s31, 0xe000
	s_nop 0
	global_load_lds_dwordx4 v[216:217], off
	s_waitcnt vmcnt(8)
	s_waitcnt lgkmcnt(0)
	s_setprio 1
	s_barrier
	v_mfma_f32_16x16x32_bf16 v[128:131], v[132:135], v[184:187], v[128:131]
	v_mfma_f32_16x16x32_bf16 v[124:127], v[140:143], v[184:187], v[124:127]
	v_mfma_f32_16x16x32_bf16 v[112:115], v[132:135], v[192:195], v[112:115]
	v_mfma_f32_16x16x32_bf16 v[108:111], v[140:143], v[192:195], v[108:111]
	v_mfma_f32_16x16x32_bf16 v[96:99], v[132:135], v[200:203], v[96:99]
	v_mfma_f32_16x16x32_bf16 v[92:95], v[140:143], v[200:203], v[92:95]
	v_mfma_f32_16x16x32_bf16 v[80:83], v[132:135], v[208:211], v[80:83]
	v_mfma_f32_16x16x32_bf16 v[76:79], v[140:143], v[208:211], v[76:79]
	v_mfma_f32_16x16x32_bf16 v[128:131], v[136:139], v[188:191], v[128:131]
	v_mfma_f32_16x16x32_bf16 v[124:127], v[144:147], v[188:191], v[124:127]
	v_mfma_f32_16x16x32_bf16 v[112:115], v[136:139], v[196:199], v[112:115]
	v_mfma_f32_16x16x32_bf16 v[108:111], v[144:147], v[196:199], v[108:111]
	v_mfma_f32_16x16x32_bf16 v[96:99], v[136:139], v[204:207], v[96:99]
	v_mfma_f32_16x16x32_bf16 v[92:95], v[144:147], v[204:207], v[92:95]
	v_mfma_f32_16x16x32_bf16 v[80:83], v[136:139], v[212:215], v[80:83]
	v_mfma_f32_16x16x32_bf16 v[76:79], v[144:147], v[212:215], v[76:79]
	v_mfma_f32_16x16x32_bf16 v[120:123], v[148:151], v[184:187], v[120:123]
	v_mfma_f32_16x16x32_bf16 v[116:119], v[166:169], v[184:187], v[116:119]
	v_mfma_f32_16x16x32_bf16 v[104:107], v[148:151], v[192:195], v[104:107]
	v_mfma_f32_16x16x32_bf16 v[100:103], v[166:169], v[192:195], v[100:103]
	v_mfma_f32_16x16x32_bf16 v[88:91], v[148:151], v[200:203], v[88:91]
	v_mfma_f32_16x16x32_bf16 v[84:87], v[166:169], v[200:203], v[84:87]
	v_mfma_f32_16x16x32_bf16 v[72:75], v[148:151], v[208:211], v[72:75]
	v_mfma_f32_16x16x32_bf16 v[68:71], v[166:169], v[208:211], v[68:71]
	v_mfma_f32_16x16x32_bf16 v[120:123], v[152:155], v[188:191], v[120:123]
	v_mfma_f32_16x16x32_bf16 v[116:119], v[170:173], v[188:191], v[116:119]
	v_mfma_f32_16x16x32_bf16 v[104:107], v[152:155], v[196:199], v[104:107]
	v_mfma_f32_16x16x32_bf16 v[100:103], v[170:173], v[196:199], v[100:103]
	v_mfma_f32_16x16x32_bf16 v[88:91], v[152:155], v[204:207], v[88:91]
	v_mfma_f32_16x16x32_bf16 v[84:87], v[170:173], v[204:207], v[84:87]
	v_mfma_f32_16x16x32_bf16 v[72:75], v[152:155], v[212:215], v[72:75]
	v_mfma_f32_16x16x32_bf16 v[68:71], v[170:173], v[212:215], v[68:71]
	s_barrier
	s_setprio 0
	s_add_i32 s16, s89, s3
	v_lshl_add_u64 v[216:217], s[28:29], 0, v[2:3]
	s_mov_b32 m0, s16
	ds_read_b128 v[184:187], v229 offset:16384
	ds_read_b128 v[188:191], v229 offset:17408
	ds_read_b128 v[192:195], v229 offset:18432
	ds_read_b128 v[196:199], v229 offset:19456
	ds_read_b128 v[200:203], v229 offset:20480
	ds_read_b128 v[204:207], v229 offset:21504
	ds_read_b128 v[208:211], v229 offset:22528
	ds_read_b128 v[212:215], v229 offset:23552
	global_load_lds_dwordx4 v[216:217], off
	s_add_i32 m0, s16, 0x2000
	s_add_u32 s16, s28, 0x80000
	v_lshl_add_u64 v[218:219], s[28:29], 0, v[156:157]
	s_addc_u32 s17, s29, 0
	s_add_i32 s89, s91, s3
	global_load_lds_dwordx4 v[218:219], off
	v_lshl_add_u64 v[220:221], s[16:17], 0, v[2:3]
	s_mov_b32 m0, s89
	v_lshl_add_u64 v[222:223], s[44:45], 0, v[158:159]
	global_load_lds_dwordx4 v[220:221], off
	v_lshl_add_u64 v[220:221], s[16:17], 0, v[156:157]
	s_add_i32 m0, s89, 0x2000
	s_nop 0
	global_load_lds_dwordx4 v[220:221], off
	v_lshl_add_u64 v[220:221], s[44:45], 0, v[160:161]
	s_mov_b32 m0, s31
	s_nop 0
	global_load_lds_dwordx4 v[220:221], off
	s_mov_b32 m0, s33
	s_nop 0
	global_load_lds_dwordx4 v[222:223], off
	s_waitcnt vmcnt(8)
	s_waitcnt lgkmcnt(0)
	s_setprio 1
	s_barrier
	v_mfma_f32_16x16x32_bf16 v[64:67], v[132:135], v[184:187], v[64:67]
	v_mfma_f32_16x16x32_bf16 v[60:63], v[140:143], v[184:187], v[60:63]
	v_mfma_f32_16x16x32_bf16 v[48:51], v[132:135], v[192:195], v[48:51]
	v_mfma_f32_16x16x32_bf16 v[44:47], v[140:143], v[192:195], v[44:47]
	v_mfma_f32_16x16x32_bf16 v[32:35], v[132:135], v[200:203], v[32:35]
	v_mfma_f32_16x16x32_bf16 v[28:31], v[140:143], v[200:203], v[28:31]
	v_mfma_f32_16x16x32_bf16 v[16:19], v[132:135], v[208:211], v[16:19]
	v_mfma_f32_16x16x32_bf16 v[12:15], v[140:143], v[208:211], v[12:15]
	v_mfma_f32_16x16x32_bf16 v[64:67], v[136:139], v[188:191], v[64:67]
	v_mfma_f32_16x16x32_bf16 v[60:63], v[144:147], v[188:191], v[60:63]
	v_mfma_f32_16x16x32_bf16 v[48:51], v[136:139], v[196:199], v[48:51]
	v_mfma_f32_16x16x32_bf16 v[44:47], v[144:147], v[196:199], v[44:47]
	v_mfma_f32_16x16x32_bf16 v[32:35], v[136:139], v[204:207], v[32:35]
	v_mfma_f32_16x16x32_bf16 v[28:31], v[144:147], v[204:207], v[28:31]
	v_mfma_f32_16x16x32_bf16 v[16:19], v[136:139], v[212:215], v[16:19]
	v_mfma_f32_16x16x32_bf16 v[12:15], v[144:147], v[212:215], v[12:15]
	v_mfma_f32_16x16x32_bf16 v[56:59], v[148:151], v[184:187], v[56:59]
	v_mfma_f32_16x16x32_bf16 v[52:55], v[166:169], v[184:187], v[52:55]
	v_mfma_f32_16x16x32_bf16 v[40:43], v[148:151], v[192:195], v[40:43]
	v_mfma_f32_16x16x32_bf16 v[36:39], v[166:169], v[192:195], v[36:39]
	v_mfma_f32_16x16x32_bf16 v[24:27], v[148:151], v[200:203], v[24:27]
	v_mfma_f32_16x16x32_bf16 v[20:23], v[166:169], v[200:203], v[20:23]
	v_mfma_f32_16x16x32_bf16 v[8:11], v[148:151], v[208:211], v[8:11]
	v_mfma_f32_16x16x32_bf16 v[4:7], v[166:169], v[208:211], v[4:7]
	v_mfma_f32_16x16x32_bf16 v[56:59], v[152:155], v[188:191], v[56:59]
	v_mfma_f32_16x16x32_bf16 v[52:55], v[170:173], v[188:191], v[52:55]
	v_mfma_f32_16x16x32_bf16 v[40:43], v[152:155], v[196:199], v[40:43]
	v_mfma_f32_16x16x32_bf16 v[36:39], v[170:173], v[196:199], v[36:39]
	v_mfma_f32_16x16x32_bf16 v[24:27], v[152:155], v[204:207], v[24:27]
	v_mfma_f32_16x16x32_bf16 v[20:23], v[170:173], v[204:207], v[20:23]
	v_mfma_f32_16x16x32_bf16 v[8:11], v[152:155], v[212:215], v[8:11]
	v_mfma_f32_16x16x32_bf16 v[4:7], v[170:173], v[212:215], v[4:7]
	s_barrier
	s_setprio 0
	s_add_i32 s89, 0, 0x18000
	s_add_i32 s91, 0, 0x1c000
	v_add_u32_e32 v144, s89, v227
	v_add_u32_e32 v170, s91, v227
	ds_read_b128 v[132:135], v144
	ds_read_b128 v[136:139], v144 offset:1024
	ds_read_b128 v[140:143], v144 offset:2048
	ds_read_b128 v[144:147], v144 offset:3072
	ds_read_b128 v[148:151], v170
	ds_read_b128 v[152:155], v170 offset:1024
	ds_read_b128 v[166:169], v170 offset:2048
	ds_read_b128 v[170:173], v170 offset:3072
	s_add_u32 s16, s44, 0x80000
	s_addc_u32 s17, s45, 0
	s_mov_b32 m0, s46
	v_lshl_add_u64 v[224:225], s[16:17], 0, v[160:161]
	ds_read_b128 v[184:187], v229 offset:32768
	ds_read_b128 v[188:191], v229 offset:33792
	ds_read_b128 v[192:195], v229 offset:34816
	ds_read_b128 v[196:199], v229 offset:35840
	ds_read_b128 v[200:203], v229 offset:36864
	ds_read_b128 v[204:207], v229 offset:37888
	ds_read_b128 v[208:211], v229 offset:38912
	ds_read_b128 v[212:215], v229 offset:39936
	global_load_lds_dwordx4 v[224:225], off
	v_lshl_add_u64 v[224:225], s[16:17], 0, v[158:159]
	s_mov_b32 m0, s47
	s_nop 0
	global_load_lds_dwordx4 v[224:225], off
	s_waitcnt vmcnt(8)
	s_waitcnt lgkmcnt(0)
	s_setprio 1
	s_barrier
	v_mfma_f32_16x16x32_bf16 v[128:131], v[132:135], v[184:187], v[128:131]
	v_mfma_f32_16x16x32_bf16 v[124:127], v[140:143], v[184:187], v[124:127]
	v_mfma_f32_16x16x32_bf16 v[112:115], v[132:135], v[192:195], v[112:115]
	v_mfma_f32_16x16x32_bf16 v[108:111], v[140:143], v[192:195], v[108:111]
	v_mfma_f32_16x16x32_bf16 v[96:99], v[132:135], v[200:203], v[96:99]
	v_mfma_f32_16x16x32_bf16 v[92:95], v[140:143], v[200:203], v[92:95]
	v_mfma_f32_16x16x32_bf16 v[80:83], v[132:135], v[208:211], v[80:83]
	v_mfma_f32_16x16x32_bf16 v[76:79], v[140:143], v[208:211], v[76:79]
	v_mfma_f32_16x16x32_bf16 v[128:131], v[136:139], v[188:191], v[128:131]
	v_mfma_f32_16x16x32_bf16 v[124:127], v[144:147], v[188:191], v[124:127]
	v_mfma_f32_16x16x32_bf16 v[112:115], v[136:139], v[196:199], v[112:115]
	v_mfma_f32_16x16x32_bf16 v[108:111], v[144:147], v[196:199], v[108:111]
	v_mfma_f32_16x16x32_bf16 v[96:99], v[136:139], v[204:207], v[96:99]
	v_mfma_f32_16x16x32_bf16 v[92:95], v[144:147], v[204:207], v[92:95]
	v_mfma_f32_16x16x32_bf16 v[80:83], v[136:139], v[212:215], v[80:83]
	v_mfma_f32_16x16x32_bf16 v[76:79], v[144:147], v[212:215], v[76:79]
	v_mfma_f32_16x16x32_bf16 v[120:123], v[148:151], v[184:187], v[120:123]
	v_mfma_f32_16x16x32_bf16 v[116:119], v[166:169], v[184:187], v[116:119]
	v_mfma_f32_16x16x32_bf16 v[104:107], v[148:151], v[192:195], v[104:107]
	v_mfma_f32_16x16x32_bf16 v[100:103], v[166:169], v[192:195], v[100:103]
	v_mfma_f32_16x16x32_bf16 v[88:91], v[148:151], v[200:203], v[88:91]
	v_mfma_f32_16x16x32_bf16 v[84:87], v[166:169], v[200:203], v[84:87]
	v_mfma_f32_16x16x32_bf16 v[72:75], v[148:151], v[208:211], v[72:75]
	v_mfma_f32_16x16x32_bf16 v[68:71], v[166:169], v[208:211], v[68:71]
	v_mfma_f32_16x16x32_bf16 v[120:123], v[152:155], v[188:191], v[120:123]
	v_mfma_f32_16x16x32_bf16 v[116:119], v[170:173], v[188:191], v[116:119]
	v_mfma_f32_16x16x32_bf16 v[104:107], v[152:155], v[196:199], v[104:107]
	v_mfma_f32_16x16x32_bf16 v[100:103], v[170:173], v[196:199], v[100:103]
	v_mfma_f32_16x16x32_bf16 v[88:91], v[152:155], v[204:207], v[88:91]
	v_mfma_f32_16x16x32_bf16 v[84:87], v[170:173], v[204:207], v[84:87]
	v_mfma_f32_16x16x32_bf16 v[72:75], v[152:155], v[212:215], v[72:75]
	v_mfma_f32_16x16x32_bf16 v[68:71], v[170:173], v[212:215], v[68:71]
	s_barrier
	s_setprio 0
	s_add_i32 s16, s89, s3
	v_lshl_add_u64 v[216:217], v[216:217], 0, s[24:25]
	s_mov_b32 m0, s16
	ds_read_b128 v[184:187], v229 offset:49152
	ds_read_b128 v[188:191], v229 offset:50176
	ds_read_b128 v[192:195], v229 offset:51200
	ds_read_b128 v[196:199], v229 offset:52224
	ds_read_b128 v[200:203], v229 offset:53248
	ds_read_b128 v[204:207], v229 offset:54272
	ds_read_b128 v[208:211], v229 offset:55296
	ds_read_b128 v[212:215], v229 offset:56320
	global_load_lds_dwordx4 v[216:217], off
	s_add_i32 m0, s16, 0x2000
	s_add_u32 s16, s28, 0x80080
	v_lshl_add_u64 v[216:217], v[218:219], 0, s[24:25]
	s_addc_u32 s17, s29, 0
	s_add_i32 s28, s91, s3
	global_load_lds_dwordx4 v[216:217], off
	v_lshl_add_u64 v[216:217], s[16:17], 0, v[2:3]
	s_mov_b32 m0, s28
	s_nop 0
	global_load_lds_dwordx4 v[216:217], off
	v_lshl_add_u64 v[216:217], s[16:17], 0, v[156:157]
	s_add_i32 m0, s28, 0x2000
	s_nop 0
	global_load_lds_dwordx4 v[216:217], off
	v_lshl_add_u64 v[216:217], v[220:221], 0, s[24:25]
	s_mov_b32 m0, s48
	s_nop 0
	global_load_lds_dwordx4 v[216:217], off
	v_lshl_add_u64 v[216:217], v[222:223], 0, s[24:25]
	s_mov_b32 m0, s49
	s_nop 0
	global_load_lds_dwordx4 v[216:217], off
	s_waitcnt vmcnt(8)
	s_waitcnt lgkmcnt(0)
	s_setprio 1
	s_barrier
	v_mfma_f32_16x16x32_bf16 v[64:67], v[132:135], v[184:187], v[64:67]
	v_mfma_f32_16x16x32_bf16 v[60:63], v[140:143], v[184:187], v[60:63]
	v_mfma_f32_16x16x32_bf16 v[48:51], v[132:135], v[192:195], v[48:51]
	v_mfma_f32_16x16x32_bf16 v[44:47], v[140:143], v[192:195], v[44:47]
	v_mfma_f32_16x16x32_bf16 v[32:35], v[132:135], v[200:203], v[32:35]
	v_mfma_f32_16x16x32_bf16 v[28:31], v[140:143], v[200:203], v[28:31]
	v_mfma_f32_16x16x32_bf16 v[16:19], v[132:135], v[208:211], v[16:19]
	v_mfma_f32_16x16x32_bf16 v[12:15], v[140:143], v[208:211], v[12:15]
	v_mfma_f32_16x16x32_bf16 v[64:67], v[136:139], v[188:191], v[64:67]
	v_mfma_f32_16x16x32_bf16 v[60:63], v[144:147], v[188:191], v[60:63]
	v_mfma_f32_16x16x32_bf16 v[48:51], v[136:139], v[196:199], v[48:51]
	v_mfma_f32_16x16x32_bf16 v[44:47], v[144:147], v[196:199], v[44:47]
	v_mfma_f32_16x16x32_bf16 v[32:35], v[136:139], v[204:207], v[32:35]
	v_mfma_f32_16x16x32_bf16 v[28:31], v[144:147], v[204:207], v[28:31]
	v_mfma_f32_16x16x32_bf16 v[16:19], v[136:139], v[212:215], v[16:19]
	v_mfma_f32_16x16x32_bf16 v[12:15], v[144:147], v[212:215], v[12:15]
	v_mfma_f32_16x16x32_bf16 v[56:59], v[148:151], v[184:187], v[56:59]
	v_mfma_f32_16x16x32_bf16 v[52:55], v[166:169], v[184:187], v[52:55]
	v_mfma_f32_16x16x32_bf16 v[40:43], v[148:151], v[192:195], v[40:43]
	v_mfma_f32_16x16x32_bf16 v[36:39], v[166:169], v[192:195], v[36:39]
	v_mfma_f32_16x16x32_bf16 v[24:27], v[148:151], v[200:203], v[24:27]
	v_mfma_f32_16x16x32_bf16 v[20:23], v[166:169], v[200:203], v[20:23]
	v_mfma_f32_16x16x32_bf16 v[8:11], v[148:151], v[208:211], v[8:11]
	v_mfma_f32_16x16x32_bf16 v[4:7], v[166:169], v[208:211], v[4:7]
	v_mfma_f32_16x16x32_bf16 v[56:59], v[152:155], v[188:191], v[56:59]
	v_mfma_f32_16x16x32_bf16 v[52:55], v[170:173], v[188:191], v[52:55]
	v_mfma_f32_16x16x32_bf16 v[40:43], v[152:155], v[196:199], v[40:43]
	v_mfma_f32_16x16x32_bf16 v[36:39], v[170:173], v[196:199], v[36:39]
	v_mfma_f32_16x16x32_bf16 v[24:27], v[152:155], v[204:207], v[24:27]
	v_mfma_f32_16x16x32_bf16 v[20:23], v[170:173], v[204:207], v[20:23]
	v_mfma_f32_16x16x32_bf16 v[8:11], v[152:155], v[212:215], v[8:11]
	v_mfma_f32_16x16x32_bf16 v[4:7], v[170:173], v[212:215], v[4:7]
	s_barrier
	s_setprio 0
	s_add_i32 s88, s88, 2
	s_add_u32 s42, s42, 0x100
	s_addc_u32 s43, s43, 0
	s_add_u32 s77, s77, 0x100
	s_addc_u32 s78, s78, 0
	s_cmp_gt_u32 s88, 29
	s_cbranch_scc0 .LBB0_205
	v_mov_b32_e32 v176, 0xc2000000
	s_and_b64 vcc, exec, s[18:19]
	s_cbranch_vccz .LBB0_208
	s_barrier

.LBB0_366:
	s_add_u32 s48, s50, 0x100
	s_addc_u32 s49, s51, 0
	s_add_i32 s16, 0, 0x10000
	s_cmpk_eq_i32 s22, 0x54
	s_cselect_b32 vcc_hi, s19, s49
	s_cselect_b32 vcc_lo, s18, s48
	s_cselect_b32 s29, s27, s33
	s_cselect_b32 s28, s26, s31
	s_add_i32 s23, 0, 0x14000
	v_add_u32_e32 v144, s16, v244
	v_add_u32_e32 v160, s23, v244
	ds_read_b128 v[132:135], v144
	ds_read_b128 v[136:139], v144 offset:1024
	ds_read_b128 v[140:143], v144 offset:2048
	ds_read_b128 v[144:147], v144 offset:3072
	ds_read_b128 v[148:151], v160
	ds_read_b128 v[152:155], v160 offset:1024
	ds_read_b128 v[156:159], v160 offset:2048
	ds_read_b128 v[160:163], v160 offset:3072
	v_lshl_add_u64 v[174:175], s[50:51], 0, v[184:185]
	s_add_i32 m0, s74, 0xc000
	ds_read_b128 v[164:167], v246
	ds_read_b128 v[188:191], v246 offset:1024
	ds_read_b128 v[192:195], v246 offset:2048
	ds_read_b128 v[196:199], v246 offset:3072
	ds_read_b128 v[200:203], v246 offset:4096
	ds_read_b128 v[204:207], v246 offset:5120
	ds_read_b128 v[208:211], v246 offset:6144
	ds_read_b128 v[212:215], v246 offset:7168
	global_load_lds_dwordx4 v[174:175], off
	v_lshl_add_u64 v[174:175], s[50:51], 0, v[186:187]
	s_add_i32 m0, s74, 0xe000
	s_nop 0
	global_load_lds_dwordx4 v[174:175], off
	s_waitcnt vmcnt(8)
	s_waitcnt lgkmcnt(0)
	s_setprio 1
	s_barrier
	v_mfma_f32_16x16x32_bf16 v[128:131], v[132:135], v[164:167], v[128:131]
	v_mfma_f32_16x16x32_bf16 v[124:127], v[140:143], v[164:167], v[124:127]
	v_mfma_f32_16x16x32_bf16 v[112:115], v[132:135], v[192:195], v[112:115]
	v_mfma_f32_16x16x32_bf16 v[108:111], v[140:143], v[192:195], v[108:111]
	v_mfma_f32_16x16x32_bf16 v[96:99], v[132:135], v[200:203], v[96:99]
	v_mfma_f32_16x16x32_bf16 v[92:95], v[140:143], v[200:203], v[92:95]
	v_mfma_f32_16x16x32_bf16 v[80:83], v[132:135], v[208:211], v[80:83]
	v_mfma_f32_16x16x32_bf16 v[76:79], v[140:143], v[208:211], v[76:79]
	v_mfma_f32_16x16x32_bf16 v[128:131], v[136:139], v[188:191], v[128:131]
	v_mfma_f32_16x16x32_bf16 v[124:127], v[144:147], v[188:191], v[124:127]
	v_mfma_f32_16x16x32_bf16 v[112:115], v[136:139], v[196:199], v[112:115]
	v_mfma_f32_16x16x32_bf16 v[108:111], v[144:147], v[196:199], v[108:111]
	v_mfma_f32_16x16x32_bf16 v[96:99], v[136:139], v[204:207], v[96:99]
	v_mfma_f32_16x16x32_bf16 v[92:95], v[144:147], v[204:207], v[92:95]
	v_mfma_f32_16x16x32_bf16 v[80:83], v[136:139], v[212:215], v[80:83]
	v_mfma_f32_16x16x32_bf16 v[76:79], v[144:147], v[212:215], v[76:79]
	v_mfma_f32_16x16x32_bf16 v[120:123], v[148:151], v[164:167], v[120:123]
	v_mfma_f32_16x16x32_bf16 v[116:119], v[156:159], v[164:167], v[116:119]
	v_mfma_f32_16x16x32_bf16 v[104:107], v[148:151], v[192:195], v[104:107]
	v_mfma_f32_16x16x32_bf16 v[100:103], v[156:159], v[192:195], v[100:103]
	v_mfma_f32_16x16x32_bf16 v[88:91], v[148:151], v[200:203], v[88:91]
	v_mfma_f32_16x16x32_bf16 v[84:87], v[156:159], v[200:203], v[84:87]
	v_mfma_f32_16x16x32_bf16 v[72:75], v[148:151], v[208:211], v[72:75]
	v_mfma_f32_16x16x32_bf16 v[68:71], v[156:159], v[208:211], v[68:71]
	v_mfma_f32_16x16x32_bf16 v[120:123], v[152:155], v[188:191], v[120:123]
	v_mfma_f32_16x16x32_bf16 v[116:119], v[160:163], v[188:191], v[116:119]
	v_mfma_f32_16x16x32_bf16 v[104:107], v[152:155], v[196:199], v[104:107]
	v_mfma_f32_16x16x32_bf16 v[100:103], v[160:163], v[196:199], v[100:103]
	v_mfma_f32_16x16x32_bf16 v[88:91], v[152:155], v[204:207], v[88:91]
	v_mfma_f32_16x16x32_bf16 v[84:87], v[160:163], v[204:207], v[84:87]
	v_mfma_f32_16x16x32_bf16 v[72:75], v[152:155], v[212:215], v[72:75]
	v_mfma_f32_16x16x32_bf16 v[68:71], v[160:163], v[212:215], v[68:71]
	s_barrier
	s_setprio 0
	s_add_i32 s16, s16, s73
	v_lshl_add_u64 v[174:175], s[28:29], 0, v[2:3]
	s_mov_b32 m0, s16
	ds_read_b128 v[164:167], v246 offset:16384
	ds_read_b128 v[188:191], v246 offset:17408
	ds_read_b128 v[192:195], v246 offset:18432
	ds_read_b128 v[196:199], v246 offset:19456
	ds_read_b128 v[200:203], v246 offset:20480
	ds_read_b128 v[204:207], v246 offset:21504
	ds_read_b128 v[208:211], v246 offset:22528
	ds_read_b128 v[212:215], v246 offset:23552
	global_load_lds_dwordx4 v[174:175], off
	s_add_i32 m0, s16, 0x2000
	s_add_u32 s16, s28, 0x58000
	v_lshl_add_u64 v[182:183], s[28:29], 0, v[168:169]
	s_addc_u32 s17, s29, 0
	s_add_i32 s23, s23, s73
	global_load_lds_dwordx4 v[182:183], off
	v_lshl_add_u64 v[216:217], s[16:17], 0, v[2:3]
	s_mov_b32 m0, s23
	v_lshl_add_u64 v[218:219], vcc, 0, v[170:171]
	global_load_lds_dwordx4 v[216:217], off
	v_lshl_add_u64 v[216:217], s[16:17], 0, v[168:169]
	s_add_i32 m0, s23, 0x2000
	s_nop 0
	global_load_lds_dwordx4 v[216:217], off
	v_lshl_add_u64 v[216:217], vcc, 0, v[172:173]
	s_mov_b32 m0, s74
	s_nop 0
	global_load_lds_dwordx4 v[216:217], off
	s_mov_b32 m0, s77
	s_nop 0
	global_load_lds_dwordx4 v[218:219], off
	s_waitcnt vmcnt(8)
	s_waitcnt lgkmcnt(0)
	s_setprio 1
	s_barrier
	v_mfma_f32_16x16x32_bf16 v[64:67], v[132:135], v[164:167], v[64:67]
	v_mfma_f32_16x16x32_bf16 v[60:63], v[140:143], v[164:167], v[60:63]
	v_mfma_f32_16x16x32_bf16 v[48:51], v[132:135], v[192:195], v[48:51]
	v_mfma_f32_16x16x32_bf16 v[44:47], v[140:143], v[192:195], v[44:47]
	v_mfma_f32_16x16x32_bf16 v[32:35], v[132:135], v[200:203], v[32:35]
	v_mfma_f32_16x16x32_bf16 v[28:31], v[140:143], v[200:203], v[28:31]
	v_mfma_f32_16x16x32_bf16 v[16:19], v[132:135], v[208:211], v[16:19]
	v_mfma_f32_16x16x32_bf16 v[12:15], v[140:143], v[208:211], v[12:15]
	v_mfma_f32_16x16x32_bf16 v[64:67], v[136:139], v[188:191], v[64:67]
	v_mfma_f32_16x16x32_bf16 v[60:63], v[144:147], v[188:191], v[60:63]
	v_mfma_f32_16x16x32_bf16 v[48:51], v[136:139], v[196:199], v[48:51]
	v_mfma_f32_16x16x32_bf16 v[44:47], v[144:147], v[196:199], v[44:47]
	v_mfma_f32_16x16x32_bf16 v[32:35], v[136:139], v[204:207], v[32:35]
	v_mfma_f32_16x16x32_bf16 v[28:31], v[144:147], v[204:207], v[28:31]
	v_mfma_f32_16x16x32_bf16 v[16:19], v[136:139], v[212:215], v[16:19]
	v_mfma_f32_16x16x32_bf16 v[12:15], v[144:147], v[212:215], v[12:15]
	v_mfma_f32_16x16x32_bf16 v[56:59], v[148:151], v[164:167], v[56:59]
	v_mfma_f32_16x16x32_bf16 v[52:55], v[156:159], v[164:167], v[52:55]
	v_mfma_f32_16x16x32_bf16 v[40:43], v[148:151], v[192:195], v[40:43]
	v_mfma_f32_16x16x32_bf16 v[36:39], v[156:159], v[192:195], v[36:39]
	v_mfma_f32_16x16x32_bf16 v[24:27], v[148:151], v[200:203], v[24:27]
	v_mfma_f32_16x16x32_bf16 v[20:23], v[156:159], v[200:203], v[20:23]
	v_mfma_f32_16x16x32_bf16 v[8:11], v[148:151], v[208:211], v[8:11]
	v_mfma_f32_16x16x32_bf16 v[4:7], v[156:159], v[208:211], v[4:7]
	v_mfma_f32_16x16x32_bf16 v[56:59], v[152:155], v[188:191], v[56:59]
	v_mfma_f32_16x16x32_bf16 v[52:55], v[160:163], v[188:191], v[52:55]
	v_mfma_f32_16x16x32_bf16 v[40:43], v[152:155], v[196:199], v[40:43]
	v_mfma_f32_16x16x32_bf16 v[36:39], v[160:163], v[196:199], v[36:39]
	v_mfma_f32_16x16x32_bf16 v[24:27], v[152:155], v[204:207], v[24:27]
	v_mfma_f32_16x16x32_bf16 v[20:23], v[160:163], v[204:207], v[20:23]
	v_mfma_f32_16x16x32_bf16 v[8:11], v[152:155], v[212:215], v[8:11]
	v_mfma_f32_16x16x32_bf16 v[4:7], v[160:163], v[212:215], v[4:7]
	s_barrier
	s_setprio 0
	s_add_i32 s23, 0, 0x18000
	s_add_i32 s50, 0, 0x1c000
	v_add_u32_e32 v144, s23, v244
	v_add_u32_e32 v160, s50, v244
	ds_read_b128 v[132:135], v144
	ds_read_b128 v[136:139], v144 offset:1024
	ds_read_b128 v[140:143], v144 offset:2048
	ds_read_b128 v[144:147], v144 offset:3072
	ds_read_b128 v[148:151], v160
	ds_read_b128 v[152:155], v160 offset:1024
	ds_read_b128 v[156:159], v160 offset:2048
	ds_read_b128 v[160:163], v160 offset:3072
	s_add_u32 s16, vcc_lo, 0x160000
	s_addc_u32 s17, vcc_hi, 0
	s_mov_b32 m0, s72
	v_lshl_add_u64 v[220:221], s[16:17], 0, v[172:173]
	ds_read_b128 v[164:167], v246 offset:32768
	ds_read_b128 v[188:191], v246 offset:33792
	ds_read_b128 v[192:195], v246 offset:34816
	ds_read_b128 v[196:199], v246 offset:35840
	ds_read_b128 v[200:203], v246 offset:36864
	ds_read_b128 v[204:207], v246 offset:37888
	ds_read_b128 v[208:211], v246 offset:38912
	ds_read_b128 v[212:215], v246 offset:39936
	global_load_lds_dwordx4 v[220:221], off
	v_lshl_add_u64 v[220:221], s[16:17], 0, v[170:171]
	s_mov_b32 m0, s78
	s_nop 0
	global_load_lds_dwordx4 v[220:221], off
	s_waitcnt vmcnt(8)
	s_waitcnt lgkmcnt(0)
	s_setprio 1
	s_barrier
	v_mfma_f32_16x16x32_bf16 v[128:131], v[132:135], v[164:167], v[128:131]
	v_mfma_f32_16x16x32_bf16 v[124:127], v[140:143], v[164:167], v[124:127]
	v_mfma_f32_16x16x32_bf16 v[112:115], v[132:135], v[192:195], v[112:115]
	v_mfma_f32_16x16x32_bf16 v[108:111], v[140:143], v[192:195], v[108:111]
	v_mfma_f32_16x16x32_bf16 v[96:99], v[132:135], v[200:203], v[96:99]
	v_mfma_f32_16x16x32_bf16 v[92:95], v[140:143], v[200:203], v[92:95]
	v_mfma_f32_16x16x32_bf16 v[80:83], v[132:135], v[208:211], v[80:83]
	v_mfma_f32_16x16x32_bf16 v[76:79], v[140:143], v[208:211], v[76:79]
	v_mfma_f32_16x16x32_bf16 v[128:131], v[136:139], v[188:191], v[128:131]
	v_mfma_f32_16x16x32_bf16 v[124:127], v[144:147], v[188:191], v[124:127]
	v_mfma_f32_16x16x32_bf16 v[112:115], v[136:139], v[196:199], v[112:115]
	v_mfma_f32_16x16x32_bf16 v[108:111], v[144:147], v[196:199], v[108:111]
	v_mfma_f32_16x16x32_bf16 v[96:99], v[136:139], v[204:207], v[96:99]
	v_mfma_f32_16x16x32_bf16 v[92:95], v[144:147], v[204:207], v[92:95]
	v_mfma_f32_16x16x32_bf16 v[80:83], v[136:139], v[212:215], v[80:83]
	v_mfma_f32_16x16x32_bf16 v[76:79], v[144:147], v[212:215], v[76:79]
	v_mfma_f32_16x16x32_bf16 v[120:123], v[148:151], v[164:167], v[120:123]
	v_mfma_f32_16x16x32_bf16 v[116:119], v[156:159], v[164:167], v[116:119]
	v_mfma_f32_16x16x32_bf16 v[104:107], v[148:151], v[192:195], v[104:107]
	v_mfma_f32_16x16x32_bf16 v[100:103], v[156:159], v[192:195], v[100:103]
	v_mfma_f32_16x16x32_bf16 v[88:91], v[148:151], v[200:203], v[88:91]
	v_mfma_f32_16x16x32_bf16 v[84:87], v[156:159], v[200:203], v[84:87]
	v_mfma_f32_16x16x32_bf16 v[72:75], v[148:151], v[208:211], v[72:75]
	v_mfma_f32_16x16x32_bf16 v[68:71], v[156:159], v[208:211], v[68:71]
	v_mfma_f32_16x16x32_bf16 v[120:123], v[152:155], v[188:191], v[120:123]
	v_mfma_f32_16x16x32_bf16 v[116:119], v[160:163], v[188:191], v[116:119]
	v_mfma_f32_16x16x32_bf16 v[104:107], v[152:155], v[196:199], v[104:107]
	v_mfma_f32_16x16x32_bf16 v[100:103], v[160:163], v[196:199], v[100:103]
	v_mfma_f32_16x16x32_bf16 v[88:91], v[152:155], v[204:207], v[88:91]
	v_mfma_f32_16x16x32_bf16 v[84:87], v[160:163], v[204:207], v[84:87]
	v_mfma_f32_16x16x32_bf16 v[72:75], v[152:155], v[212:215], v[72:75]
	v_mfma_f32_16x16x32_bf16 v[68:71], v[160:163], v[212:215], v[68:71]
	s_barrier
	s_setprio 0
	s_add_i32 s16, s23, s73
	v_lshl_add_u64 v[174:175], v[174:175], 0, s[24:25]
	s_mov_b32 m0, s16
	ds_read_b128 v[164:167], v246 offset:49152
	ds_read_b128 v[188:191], v246 offset:50176
	ds_read_b128 v[192:195], v246 offset:51200
	ds_read_b128 v[196:199], v246 offset:52224
	ds_read_b128 v[200:203], v246 offset:53248
	ds_read_b128 v[204:207], v246 offset:54272
	ds_read_b128 v[208:211], v246 offset:55296
	ds_read_b128 v[212:215], v246 offset:56320
	global_load_lds_dwordx4 v[174:175], off
	s_add_i32 m0, s16, 0x2000
	s_add_u32 s16, s28, 0x58080
	v_lshl_add_u64 v[174:175], v[182:183], 0, s[24:25]
	s_addc_u32 s17, s29, 0
	s_add_i32 s23, s50, s73
	global_load_lds_dwordx4 v[174:175], off
	v_lshl_add_u64 v[174:175], s[16:17], 0, v[2:3]
	s_mov_b32 m0, s23
	s_nop 0
	global_load_lds_dwordx4 v[174:175], off
	v_lshl_add_u64 v[174:175], s[16:17], 0, v[168:169]
	s_add_i32 m0, s23, 0x2000
	s_nop 0
	global_load_lds_dwordx4 v[174:175], off
	v_lshl_add_u64 v[174:175], v[216:217], 0, s[24:25]
	s_mov_b32 m0, s36
	s_nop 0
	global_load_lds_dwordx4 v[174:175], off
	v_lshl_add_u64 v[174:175], v[218:219], 0, s[24:25]
	s_mov_b32 m0, s37
	s_nop 0
	global_load_lds_dwordx4 v[174:175], off
	s_waitcnt vmcnt(8)
	s_waitcnt lgkmcnt(0)
	s_setprio 1
	s_barrier
	v_mfma_f32_16x16x32_bf16 v[64:67], v[132:135], v[164:167], v[64:67]
	v_mfma_f32_16x16x32_bf16 v[60:63], v[140:143], v[164:167], v[60:63]
	v_mfma_f32_16x16x32_bf16 v[48:51], v[132:135], v[192:195], v[48:51]
	v_mfma_f32_16x16x32_bf16 v[44:47], v[140:143], v[192:195], v[44:47]
	v_mfma_f32_16x16x32_bf16 v[32:35], v[132:135], v[200:203], v[32:35]
	v_mfma_f32_16x16x32_bf16 v[28:31], v[140:143], v[200:203], v[28:31]
	v_mfma_f32_16x16x32_bf16 v[16:19], v[132:135], v[208:211], v[16:19]
	v_mfma_f32_16x16x32_bf16 v[12:15], v[140:143], v[208:211], v[12:15]
	v_mfma_f32_16x16x32_bf16 v[64:67], v[136:139], v[188:191], v[64:67]
	v_mfma_f32_16x16x32_bf16 v[60:63], v[144:147], v[188:191], v[60:63]
	v_mfma_f32_16x16x32_bf16 v[48:51], v[136:139], v[196:199], v[48:51]
	v_mfma_f32_16x16x32_bf16 v[44:47], v[144:147], v[196:199], v[44:47]
	v_mfma_f32_16x16x32_bf16 v[32:35], v[136:139], v[204:207], v[32:35]
	v_mfma_f32_16x16x32_bf16 v[28:31], v[144:147], v[204:207], v[28:31]
	v_mfma_f32_16x16x32_bf16 v[16:19], v[136:139], v[212:215], v[16:19]
	v_mfma_f32_16x16x32_bf16 v[12:15], v[144:147], v[212:215], v[12:15]
	v_mfma_f32_16x16x32_bf16 v[56:59], v[148:151], v[164:167], v[56:59]
	v_mfma_f32_16x16x32_bf16 v[52:55], v[156:159], v[164:167], v[52:55]
	v_mfma_f32_16x16x32_bf16 v[40:43], v[148:151], v[192:195], v[40:43]
	v_mfma_f32_16x16x32_bf16 v[36:39], v[156:159], v[192:195], v[36:39]
	v_mfma_f32_16x16x32_bf16 v[24:27], v[148:151], v[200:203], v[24:27]
	v_mfma_f32_16x16x32_bf16 v[20:23], v[156:159], v[200:203], v[20:23]
	v_mfma_f32_16x16x32_bf16 v[8:11], v[148:151], v[208:211], v[8:11]
	v_mfma_f32_16x16x32_bf16 v[4:7], v[156:159], v[208:211], v[4:7]
	v_mfma_f32_16x16x32_bf16 v[56:59], v[152:155], v[188:191], v[56:59]
	v_mfma_f32_16x16x32_bf16 v[52:55], v[160:163], v[188:191], v[52:55]
	v_mfma_f32_16x16x32_bf16 v[40:43], v[152:155], v[196:199], v[40:43]
	v_mfma_f32_16x16x32_bf16 v[36:39], v[160:163], v[196:199], v[36:39]
	v_mfma_f32_16x16x32_bf16 v[24:27], v[152:155], v[204:207], v[24:27]
	v_mfma_f32_16x16x32_bf16 v[20:23], v[160:163], v[204:207], v[20:23]
	v_mfma_f32_16x16x32_bf16 v[8:11], v[152:155], v[212:215], v[8:11]
	v_mfma_f32_16x16x32_bf16 v[4:7], v[160:163], v[212:215], v[4:7]
	s_barrier
	s_setprio 0
	s_add_i32 s22, s22, 2
	s_add_u32 s31, s31, 0x100
	s_addc_u32 s33, s33, 0
	s_cmpk_gt_u32 s22, 0x55
	s_mov_b64 s[50:51], s[48:49]
	s_cbranch_scc0 .LBB0_366
	v_readlane_b32 s16, v252, 12
	v_readlane_b32 s17, v252, 13
	s_and_b64 vcc, exec, s[16:17]
	s_cbranch_vccz .LBB0_369
	s_barrier

.LBB0_446:
	s_add_u32 s16, s44, 0xfff80080
	s_addc_u32 s17, s45, -1
	s_add_i32 s94, 0, 0x10000
	s_cmp_eq_u32 vcc_lo, 28
	s_cselect_b32 s47, s37, s17
	s_cselect_b32 s46, s88, s16
	s_cselect_b32 s29, s27, s96
	s_cselect_b32 s28, s89, s91
	s_add_i32 s95, 0, 0x14000
	v_add_u32_e32 v144, s94, v219
	v_add_u32_e32 v172, s95, v219
	ds_read_b128 v[132:135], v144
	ds_read_b128 v[136:139], v144 offset:1024
	ds_read_b128 v[140:143], v144 offset:2048
	ds_read_b128 v[144:147], v144 offset:3072
	ds_read_b128 v[148:151], v172
	ds_read_b128 v[164:167], v172 offset:1024
	ds_read_b128 v[168:171], v172 offset:2048
	ds_read_b128 v[184:187], v172 offset:3072
	v_lshl_add_u64 v[172:173], s[44:45], 0, v[160:161]
	s_add_i32 m0, s48, 0xc000
	ds_read_b128 v[188:191], v221
	ds_read_b128 v[192:195], v221 offset:1024
	ds_read_b128 v[196:199], v221 offset:2048
	ds_read_b128 v[200:203], v221 offset:3072
	ds_read_b128 v[204:207], v221 offset:4096
	ds_read_b128 v[208:211], v221 offset:5120
	ds_read_b128 v[212:215], v221 offset:6144
	ds_read_b128 v[222:225], v221 offset:7168
	global_load_lds_dwordx4 v[172:173], off
	v_lshl_add_u64 v[172:173], s[44:45], 0, v[162:163]
	s_add_i32 m0, s48, 0xe000
	s_nop 0
	global_load_lds_dwordx4 v[172:173], off
	s_waitcnt vmcnt(8)
	s_waitcnt lgkmcnt(0)
	s_setprio 1
	s_barrier
	v_mfma_f32_16x16x32_bf16 v[128:131], v[132:135], v[188:191], v[128:131]
	v_mfma_f32_16x16x32_bf16 v[124:127], v[140:143], v[188:191], v[124:127]
	v_mfma_f32_16x16x32_bf16 v[112:115], v[132:135], v[196:199], v[112:115]
	v_mfma_f32_16x16x32_bf16 v[108:111], v[140:143], v[196:199], v[108:111]
	v_mfma_f32_16x16x32_bf16 v[96:99], v[132:135], v[204:207], v[96:99]
	v_mfma_f32_16x16x32_bf16 v[92:95], v[140:143], v[204:207], v[92:95]
	v_mfma_f32_16x16x32_bf16 v[80:83], v[132:135], v[212:215], v[80:83]
	v_mfma_f32_16x16x32_bf16 v[76:79], v[140:143], v[212:215], v[76:79]
	v_mfma_f32_16x16x32_bf16 v[128:131], v[136:139], v[192:195], v[128:131]
	v_mfma_f32_16x16x32_bf16 v[124:127], v[144:147], v[192:195], v[124:127]
	v_mfma_f32_16x16x32_bf16 v[112:115], v[136:139], v[200:203], v[112:115]
	v_mfma_f32_16x16x32_bf16 v[108:111], v[144:147], v[200:203], v[108:111]
	v_mfma_f32_16x16x32_bf16 v[96:99], v[136:139], v[208:211], v[96:99]
	v_mfma_f32_16x16x32_bf16 v[92:95], v[144:147], v[208:211], v[92:95]
	v_mfma_f32_16x16x32_bf16 v[80:83], v[136:139], v[222:225], v[80:83]
	v_mfma_f32_16x16x32_bf16 v[76:79], v[144:147], v[222:225], v[76:79]
	v_mfma_f32_16x16x32_bf16 v[120:123], v[148:151], v[188:191], v[120:123]
	v_mfma_f32_16x16x32_bf16 v[116:119], v[168:171], v[188:191], v[116:119]
	v_mfma_f32_16x16x32_bf16 v[104:107], v[148:151], v[196:199], v[104:107]
	v_mfma_f32_16x16x32_bf16 v[100:103], v[168:171], v[196:199], v[100:103]
	v_mfma_f32_16x16x32_bf16 v[88:91], v[148:151], v[204:207], v[88:91]
	v_mfma_f32_16x16x32_bf16 v[84:87], v[168:171], v[204:207], v[84:87]
	v_mfma_f32_16x16x32_bf16 v[72:75], v[148:151], v[212:215], v[72:75]
	v_mfma_f32_16x16x32_bf16 v[68:71], v[168:171], v[212:215], v[68:71]
	v_mfma_f32_16x16x32_bf16 v[120:123], v[164:167], v[192:195], v[120:123]
	v_mfma_f32_16x16x32_bf16 v[116:119], v[184:187], v[192:195], v[116:119]
	v_mfma_f32_16x16x32_bf16 v[104:107], v[164:167], v[200:203], v[104:107]
	v_mfma_f32_16x16x32_bf16 v[100:103], v[184:187], v[200:203], v[100:103]
	v_mfma_f32_16x16x32_bf16 v[88:91], v[164:167], v[208:211], v[88:91]
	v_mfma_f32_16x16x32_bf16 v[84:87], v[184:187], v[208:211], v[84:87]
	v_mfma_f32_16x16x32_bf16 v[72:75], v[164:167], v[222:225], v[72:75]
	v_mfma_f32_16x16x32_bf16 v[68:71], v[184:187], v[222:225], v[68:71]
	s_barrier
	s_setprio 0
	s_add_i32 s16, s94, s33
	v_lshl_add_u64 v[172:173], s[28:29], 0, v[2:3]
	s_mov_b32 m0, s16
	ds_read_b128 v[188:191], v221 offset:16384
	ds_read_b128 v[192:195], v221 offset:17408
	ds_read_b128 v[196:199], v221 offset:18432
	ds_read_b128 v[200:203], v221 offset:19456
	ds_read_b128 v[204:207], v221 offset:20480
	ds_read_b128 v[208:211], v221 offset:21504
	ds_read_b128 v[212:215], v221 offset:22528
	ds_read_b128 v[222:225], v221 offset:23552
	global_load_lds_dwordx4 v[172:173], off
	s_add_i32 m0, s16, 0x2000
	s_add_u32 s16, s28, 0x80000
	v_lshl_add_u64 v[174:175], s[28:29], 0, v[152:153]
	s_addc_u32 s17, s29, 0
	s_add_i32 s94, s95, s33
	global_load_lds_dwordx4 v[174:175], off
	v_lshl_add_u64 v[182:183], s[16:17], 0, v[2:3]
	s_mov_b32 m0, s94
	v_lshl_add_u64 v[216:217], s[46:47], 0, v[154:155]
	global_load_lds_dwordx4 v[182:183], off
	v_lshl_add_u64 v[182:183], s[16:17], 0, v[152:153]
	s_add_i32 m0, s94, 0x2000
	s_nop 0
	global_load_lds_dwordx4 v[182:183], off
	v_lshl_add_u64 v[182:183], s[46:47], 0, v[156:157]
	s_mov_b32 m0, s48
	s_nop 0
	global_load_lds_dwordx4 v[182:183], off
	s_mov_b32 m0, s49
	s_nop 0
	global_load_lds_dwordx4 v[216:217], off
	s_waitcnt vmcnt(8)
	s_waitcnt lgkmcnt(0)
	s_setprio 1
	s_barrier
	v_mfma_f32_16x16x32_bf16 v[64:67], v[132:135], v[188:191], v[64:67]
	v_mfma_f32_16x16x32_bf16 v[60:63], v[140:143], v[188:191], v[60:63]
	v_mfma_f32_16x16x32_bf16 v[48:51], v[132:135], v[196:199], v[48:51]
	v_mfma_f32_16x16x32_bf16 v[44:47], v[140:143], v[196:199], v[44:47]
	v_mfma_f32_16x16x32_bf16 v[32:35], v[132:135], v[204:207], v[32:35]
	v_mfma_f32_16x16x32_bf16 v[28:31], v[140:143], v[204:207], v[28:31]
	v_mfma_f32_16x16x32_bf16 v[16:19], v[132:135], v[212:215], v[16:19]
	v_mfma_f32_16x16x32_bf16 v[12:15], v[140:143], v[212:215], v[12:15]
	v_mfma_f32_16x16x32_bf16 v[64:67], v[136:139], v[192:195], v[64:67]
	v_mfma_f32_16x16x32_bf16 v[60:63], v[144:147], v[192:195], v[60:63]
	v_mfma_f32_16x16x32_bf16 v[48:51], v[136:139], v[200:203], v[48:51]
	v_mfma_f32_16x16x32_bf16 v[44:47], v[144:147], v[200:203], v[44:47]
	v_mfma_f32_16x16x32_bf16 v[32:35], v[136:139], v[208:211], v[32:35]
	v_mfma_f32_16x16x32_bf16 v[28:31], v[144:147], v[208:211], v[28:31]
	v_mfma_f32_16x16x32_bf16 v[16:19], v[136:139], v[222:225], v[16:19]
	v_mfma_f32_16x16x32_bf16 v[12:15], v[144:147], v[222:225], v[12:15]
	v_mfma_f32_16x16x32_bf16 v[56:59], v[148:151], v[188:191], v[56:59]
	v_mfma_f32_16x16x32_bf16 v[52:55], v[168:171], v[188:191], v[52:55]
	v_mfma_f32_16x16x32_bf16 v[40:43], v[148:151], v[196:199], v[40:43]
	v_mfma_f32_16x16x32_bf16 v[36:39], v[168:171], v[196:199], v[36:39]
	v_mfma_f32_16x16x32_bf16 v[24:27], v[148:151], v[204:207], v[24:27]
	v_mfma_f32_16x16x32_bf16 v[20:23], v[168:171], v[204:207], v[20:23]
	v_mfma_f32_16x16x32_bf16 v[8:11], v[148:151], v[212:215], v[8:11]
	v_mfma_f32_16x16x32_bf16 v[4:7], v[168:171], v[212:215], v[4:7]
	v_mfma_f32_16x16x32_bf16 v[56:59], v[164:167], v[192:195], v[56:59]
	v_mfma_f32_16x16x32_bf16 v[52:55], v[184:187], v[192:195], v[52:55]
	v_mfma_f32_16x16x32_bf16 v[40:43], v[164:167], v[200:203], v[40:43]
	v_mfma_f32_16x16x32_bf16 v[36:39], v[184:187], v[200:203], v[36:39]
	v_mfma_f32_16x16x32_bf16 v[24:27], v[164:167], v[208:211], v[24:27]
	v_mfma_f32_16x16x32_bf16 v[20:23], v[184:187], v[208:211], v[20:23]
	v_mfma_f32_16x16x32_bf16 v[8:11], v[164:167], v[222:225], v[8:11]
	v_mfma_f32_16x16x32_bf16 v[4:7], v[184:187], v[222:225], v[4:7]
	s_barrier
	s_setprio 0
	s_add_i32 s94, 0, 0x18000
	s_add_i32 s95, 0, 0x1c000
	v_add_u32_e32 v144, s94, v219
	v_add_u32_e32 v176, s95, v219
	ds_read_b128 v[132:135], v144
	ds_read_b128 v[136:139], v144 offset:1024
	ds_read_b128 v[140:143], v144 offset:2048
	ds_read_b128 v[144:147], v144 offset:3072
	ds_read_b128 v[148:151], v176
	ds_read_b128 v[164:167], v176 offset:1024
	ds_read_b128 v[168:171], v176 offset:2048
	ds_read_b128 v[184:187], v176 offset:3072
	s_add_u32 s16, s46, 0x80000
	s_addc_u32 s17, s47, 0
	s_mov_b32 m0, s50
	v_lshl_add_u64 v[226:227], s[16:17], 0, v[156:157]
	ds_read_b128 v[188:191], v221 offset:32768
	ds_read_b128 v[192:195], v221 offset:33792
	ds_read_b128 v[196:199], v221 offset:34816
	ds_read_b128 v[200:203], v221 offset:35840
	ds_read_b128 v[204:207], v221 offset:36864
	ds_read_b128 v[208:211], v221 offset:37888
	ds_read_b128 v[212:215], v221 offset:38912
	ds_read_b128 v[222:225], v221 offset:39936
	global_load_lds_dwordx4 v[226:227], off
	v_lshl_add_u64 v[226:227], s[16:17], 0, v[154:155]
	s_mov_b32 m0, s51
	s_nop 0
	global_load_lds_dwordx4 v[226:227], off
	s_waitcnt vmcnt(8)
	s_waitcnt lgkmcnt(0)
	s_setprio 1
	s_barrier
	v_mfma_f32_16x16x32_bf16 v[128:131], v[132:135], v[188:191], v[128:131]
	v_mfma_f32_16x16x32_bf16 v[124:127], v[140:143], v[188:191], v[124:127]
	v_mfma_f32_16x16x32_bf16 v[112:115], v[132:135], v[196:199], v[112:115]
	v_mfma_f32_16x16x32_bf16 v[108:111], v[140:143], v[196:199], v[108:111]
	v_mfma_f32_16x16x32_bf16 v[96:99], v[132:135], v[204:207], v[96:99]
	v_mfma_f32_16x16x32_bf16 v[92:95], v[140:143], v[204:207], v[92:95]
	v_mfma_f32_16x16x32_bf16 v[80:83], v[132:135], v[212:215], v[80:83]
	v_mfma_f32_16x16x32_bf16 v[76:79], v[140:143], v[212:215], v[76:79]
	v_mfma_f32_16x16x32_bf16 v[128:131], v[136:139], v[192:195], v[128:131]
	v_mfma_f32_16x16x32_bf16 v[124:127], v[144:147], v[192:195], v[124:127]
	v_mfma_f32_16x16x32_bf16 v[112:115], v[136:139], v[200:203], v[112:115]
	v_mfma_f32_16x16x32_bf16 v[108:111], v[144:147], v[200:203], v[108:111]
	v_mfma_f32_16x16x32_bf16 v[96:99], v[136:139], v[208:211], v[96:99]
	v_mfma_f32_16x16x32_bf16 v[92:95], v[144:147], v[208:211], v[92:95]
	v_mfma_f32_16x16x32_bf16 v[80:83], v[136:139], v[222:225], v[80:83]
	v_mfma_f32_16x16x32_bf16 v[76:79], v[144:147], v[222:225], v[76:79]
	v_mfma_f32_16x16x32_bf16 v[120:123], v[148:151], v[188:191], v[120:123]
	v_mfma_f32_16x16x32_bf16 v[116:119], v[168:171], v[188:191], v[116:119]
	v_mfma_f32_16x16x32_bf16 v[104:107], v[148:151], v[196:199], v[104:107]
	v_mfma_f32_16x16x32_bf16 v[100:103], v[168:171], v[196:199], v[100:103]
	v_mfma_f32_16x16x32_bf16 v[88:91], v[148:151], v[204:207], v[88:91]
	v_mfma_f32_16x16x32_bf16 v[84:87], v[168:171], v[204:207], v[84:87]
	v_mfma_f32_16x16x32_bf16 v[72:75], v[148:151], v[212:215], v[72:75]
	v_mfma_f32_16x16x32_bf16 v[68:71], v[168:171], v[212:215], v[68:71]
	v_mfma_f32_16x16x32_bf16 v[120:123], v[164:167], v[192:195], v[120:123]
	v_mfma_f32_16x16x32_bf16 v[116:119], v[184:187], v[192:195], v[116:119]
	v_mfma_f32_16x16x32_bf16 v[104:107], v[164:167], v[200:203], v[104:107]
	v_mfma_f32_16x16x32_bf16 v[100:103], v[184:187], v[200:203], v[100:103]
	v_mfma_f32_16x16x32_bf16 v[88:91], v[164:167], v[208:211], v[88:91]
	v_mfma_f32_16x16x32_bf16 v[84:87], v[184:187], v[208:211], v[84:87]
	v_mfma_f32_16x16x32_bf16 v[72:75], v[164:167], v[222:225], v[72:75]
	v_mfma_f32_16x16x32_bf16 v[68:71], v[184:187], v[222:225], v[68:71]
	s_barrier
	s_setprio 0
	s_add_i32 s16, s94, s33
	v_lshl_add_u64 v[172:173], v[172:173], 0, s[24:25]
	s_mov_b32 m0, s16
	ds_read_b128 v[188:191], v221 offset:49152
	ds_read_b128 v[192:195], v221 offset:50176
	ds_read_b128 v[196:199], v221 offset:51200
	ds_read_b128 v[200:203], v221 offset:52224
	ds_read_b128 v[204:207], v221 offset:53248
	ds_read_b128 v[208:211], v221 offset:54272
	ds_read_b128 v[212:215], v221 offset:55296
	ds_read_b128 v[222:225], v221 offset:56320
	global_load_lds_dwordx4 v[172:173], off
	s_add_i32 m0, s16, 0x2000
	s_add_u32 s16, s28, 0x80080
	v_lshl_add_u64 v[172:173], v[174:175], 0, s[24:25]
	s_addc_u32 s17, s29, 0
	s_add_i32 s28, s95, s33
	global_load_lds_dwordx4 v[172:173], off
	v_lshl_add_u64 v[172:173], s[16:17], 0, v[2:3]
	s_mov_b32 m0, s28
	s_nop 0
	global_load_lds_dwordx4 v[172:173], off
	v_lshl_add_u64 v[172:173], s[16:17], 0, v[152:153]
	s_add_i32 m0, s28, 0x2000
	s_nop 0
	global_load_lds_dwordx4 v[172:173], off
	v_lshl_add_u64 v[172:173], v[182:183], 0, s[24:25]
	s_mov_b32 m0, s72
	s_nop 0
	global_load_lds_dwordx4 v[172:173], off
	v_lshl_add_u64 v[172:173], v[216:217], 0, s[24:25]
	s_mov_b32 m0, s73
	s_nop 0
	global_load_lds_dwordx4 v[172:173], off
	s_waitcnt vmcnt(8)
	s_waitcnt lgkmcnt(0)
	s_setprio 1
	s_barrier
	v_mfma_f32_16x16x32_bf16 v[64:67], v[132:135], v[188:191], v[64:67]
	v_mfma_f32_16x16x32_bf16 v[60:63], v[140:143], v[188:191], v[60:63]
	v_mfma_f32_16x16x32_bf16 v[48:51], v[132:135], v[196:199], v[48:51]
	v_mfma_f32_16x16x32_bf16 v[44:47], v[140:143], v[196:199], v[44:47]
	v_mfma_f32_16x16x32_bf16 v[32:35], v[132:135], v[204:207], v[32:35]
	v_mfma_f32_16x16x32_bf16 v[28:31], v[140:143], v[204:207], v[28:31]
	v_mfma_f32_16x16x32_bf16 v[16:19], v[132:135], v[212:215], v[16:19]
	v_mfma_f32_16x16x32_bf16 v[12:15], v[140:143], v[212:215], v[12:15]
	v_mfma_f32_16x16x32_bf16 v[64:67], v[136:139], v[192:195], v[64:67]
	v_mfma_f32_16x16x32_bf16 v[60:63], v[144:147], v[192:195], v[60:63]
	v_mfma_f32_16x16x32_bf16 v[48:51], v[136:139], v[200:203], v[48:51]
	v_mfma_f32_16x16x32_bf16 v[44:47], v[144:147], v[200:203], v[44:47]
	v_mfma_f32_16x16x32_bf16 v[32:35], v[136:139], v[208:211], v[32:35]
	v_mfma_f32_16x16x32_bf16 v[28:31], v[144:147], v[208:211], v[28:31]
	v_mfma_f32_16x16x32_bf16 v[16:19], v[136:139], v[222:225], v[16:19]
	v_mfma_f32_16x16x32_bf16 v[12:15], v[144:147], v[222:225], v[12:15]
	v_mfma_f32_16x16x32_bf16 v[56:59], v[148:151], v[188:191], v[56:59]
	v_mfma_f32_16x16x32_bf16 v[52:55], v[168:171], v[188:191], v[52:55]
	v_mfma_f32_16x16x32_bf16 v[40:43], v[148:151], v[196:199], v[40:43]
	v_mfma_f32_16x16x32_bf16 v[36:39], v[168:171], v[196:199], v[36:39]
	v_mfma_f32_16x16x32_bf16 v[24:27], v[148:151], v[204:207], v[24:27]
	v_mfma_f32_16x16x32_bf16 v[20:23], v[168:171], v[204:207], v[20:23]
	v_mfma_f32_16x16x32_bf16 v[8:11], v[148:151], v[212:215], v[8:11]
	v_mfma_f32_16x16x32_bf16 v[4:7], v[168:171], v[212:215], v[4:7]
	v_mfma_f32_16x16x32_bf16 v[56:59], v[164:167], v[192:195], v[56:59]
	v_mfma_f32_16x16x32_bf16 v[52:55], v[184:187], v[192:195], v[52:55]
	v_mfma_f32_16x16x32_bf16 v[40:43], v[164:167], v[200:203], v[40:43]
	v_mfma_f32_16x16x32_bf16 v[36:39], v[184:187], v[200:203], v[36:39]
	v_mfma_f32_16x16x32_bf16 v[24:27], v[164:167], v[208:211], v[24:27]
	v_mfma_f32_16x16x32_bf16 v[20:23], v[184:187], v[208:211], v[20:23]
	v_mfma_f32_16x16x32_bf16 v[8:11], v[164:167], v[222:225], v[8:11]
	v_mfma_f32_16x16x32_bf16 v[4:7], v[184:187], v[222:225], v[4:7]
	s_barrier
	s_setprio 0
	s_add_i32 vcc_lo, vcc_lo, 2
	s_add_u32 s44, s44, 0x100
	s_addc_u32 s45, s45, 0
	s_add_u32 s91, s91, 0x100
	s_addc_u32 s96, s96, 0
	s_cmp_gt_u32 vcc_lo, 29
	s_cbranch_scc0 .LBB0_446
	v_mov_b32_e32 v250, 0xc2000000
	v_mov_b32_e32 v1, 0xbfb8aa3b
	v_mov_b64_e32 v[238:239], v[236:237]
	s_and_b64 vcc, exec, s[22:23]
	s_cbranch_vccz .LBB0_449
	s_barrier

.LBB0_790:
	s_add_u32 s11, vcc_lo, 0xfff80080
	s_addc_u32 s16, vcc_hi, -1
	s_add_i32 s17, 0, 0x10000
	s_cmp_eq_u32 s10, 28
	s_cselect_b32 s73, s19, s16
	s_cselect_b32 s72, s31, s11
	s_cselect_b32 s29, s23, s49
	s_cselect_b32 s28, s33, s48
	s_add_i32 s11, 0, 0x14000
	v_add_u32_e32 v144, s17, v244
	v_add_u32_e32 v160, s11, v244
	ds_read_b128 v[132:135], v144
	ds_read_b128 v[136:139], v144 offset:1024
	ds_read_b128 v[140:143], v144 offset:2048
	ds_read_b128 v[144:147], v144 offset:3072
	ds_read_b128 v[148:151], v160
	ds_read_b128 v[152:155], v160 offset:1024
	ds_read_b128 v[156:159], v160 offset:2048
	ds_read_b128 v[160:163], v160 offset:3072
	v_lshl_add_u64 v[174:175], vcc, 0, v[184:185]
	s_add_i32 m0, s77, 0xc000
	ds_read_b128 v[164:167], v246
	ds_read_b128 v[188:191], v246 offset:1024
	ds_read_b128 v[192:195], v246 offset:2048
	ds_read_b128 v[196:199], v246 offset:3072
	ds_read_b128 v[200:203], v246 offset:4096
	ds_read_b128 v[204:207], v246 offset:5120
	ds_read_b128 v[208:211], v246 offset:6144
	ds_read_b128 v[212:215], v246 offset:7168
	global_load_lds_dwordx4 v[174:175], off
	v_lshl_add_u64 v[174:175], vcc, 0, v[186:187]
	s_add_i32 m0, s77, 0xe000
	s_nop 0
	global_load_lds_dwordx4 v[174:175], off
	s_waitcnt vmcnt(8)
	s_waitcnt lgkmcnt(0)
	s_setprio 1
	s_barrier
	v_mfma_f32_16x16x32_bf16 v[128:131], v[132:135], v[164:167], v[128:131]
	v_mfma_f32_16x16x32_bf16 v[124:127], v[140:143], v[164:167], v[124:127]
	v_mfma_f32_16x16x32_bf16 v[112:115], v[132:135], v[192:195], v[112:115]
	v_mfma_f32_16x16x32_bf16 v[108:111], v[140:143], v[192:195], v[108:111]
	v_mfma_f32_16x16x32_bf16 v[96:99], v[132:135], v[200:203], v[96:99]
	v_mfma_f32_16x16x32_bf16 v[92:95], v[140:143], v[200:203], v[92:95]
	v_mfma_f32_16x16x32_bf16 v[80:83], v[132:135], v[208:211], v[80:83]
	v_mfma_f32_16x16x32_bf16 v[76:79], v[140:143], v[208:211], v[76:79]
	v_mfma_f32_16x16x32_bf16 v[128:131], v[136:139], v[188:191], v[128:131]
	v_mfma_f32_16x16x32_bf16 v[124:127], v[144:147], v[188:191], v[124:127]
	v_mfma_f32_16x16x32_bf16 v[112:115], v[136:139], v[196:199], v[112:115]
	v_mfma_f32_16x16x32_bf16 v[108:111], v[144:147], v[196:199], v[108:111]
	v_mfma_f32_16x16x32_bf16 v[96:99], v[136:139], v[204:207], v[96:99]
	v_mfma_f32_16x16x32_bf16 v[92:95], v[144:147], v[204:207], v[92:95]
	v_mfma_f32_16x16x32_bf16 v[80:83], v[136:139], v[212:215], v[80:83]
	v_mfma_f32_16x16x32_bf16 v[76:79], v[144:147], v[212:215], v[76:79]
	v_mfma_f32_16x16x32_bf16 v[120:123], v[148:151], v[164:167], v[120:123]
	v_mfma_f32_16x16x32_bf16 v[116:119], v[156:159], v[164:167], v[116:119]
	v_mfma_f32_16x16x32_bf16 v[104:107], v[148:151], v[192:195], v[104:107]
	v_mfma_f32_16x16x32_bf16 v[100:103], v[156:159], v[192:195], v[100:103]
	v_mfma_f32_16x16x32_bf16 v[88:91], v[148:151], v[200:203], v[88:91]
	v_mfma_f32_16x16x32_bf16 v[84:87], v[156:159], v[200:203], v[84:87]
	v_mfma_f32_16x16x32_bf16 v[72:75], v[148:151], v[208:211], v[72:75]
	v_mfma_f32_16x16x32_bf16 v[68:71], v[156:159], v[208:211], v[68:71]
	v_mfma_f32_16x16x32_bf16 v[120:123], v[152:155], v[188:191], v[120:123]
	v_mfma_f32_16x16x32_bf16 v[116:119], v[160:163], v[188:191], v[116:119]
	v_mfma_f32_16x16x32_bf16 v[104:107], v[152:155], v[196:199], v[104:107]
	v_mfma_f32_16x16x32_bf16 v[100:103], v[160:163], v[196:199], v[100:103]
	v_mfma_f32_16x16x32_bf16 v[88:91], v[152:155], v[204:207], v[88:91]
	v_mfma_f32_16x16x32_bf16 v[84:87], v[160:163], v[204:207], v[84:87]
	v_mfma_f32_16x16x32_bf16 v[72:75], v[152:155], v[212:215], v[72:75]
	v_mfma_f32_16x16x32_bf16 v[68:71], v[160:163], v[212:215], v[68:71]
	s_barrier
	s_setprio 0
	s_add_i32 s16, s17, s74
	v_lshl_add_u64 v[174:175], s[28:29], 0, v[2:3]
	s_mov_b32 m0, s16
	ds_read_b128 v[164:167], v246 offset:16384
	ds_read_b128 v[188:191], v246 offset:17408
	ds_read_b128 v[192:195], v246 offset:18432
	ds_read_b128 v[196:199], v246 offset:19456
	ds_read_b128 v[200:203], v246 offset:20480
	ds_read_b128 v[204:207], v246 offset:21504
	ds_read_b128 v[208:211], v246 offset:22528
	ds_read_b128 v[212:215], v246 offset:23552
	global_load_lds_dwordx4 v[174:175], off
	s_add_i32 m0, s16, 0x2000
	s_add_u32 s16, s28, 0x20000
	v_lshl_add_u64 v[176:177], s[28:29], 0, v[168:169]
	s_addc_u32 s17, s29, 0
	s_add_i32 s11, s11, s74
	global_load_lds_dwordx4 v[176:177], off
	v_lshl_add_u64 v[178:179], s[16:17], 0, v[2:3]
	s_mov_b32 m0, s11
	v_lshl_add_u64 v[180:181], s[72:73], 0, v[170:171]
	global_load_lds_dwordx4 v[178:179], off
	v_lshl_add_u64 v[178:179], s[16:17], 0, v[168:169]
	s_add_i32 m0, s11, 0x2000
	s_nop 0
	global_load_lds_dwordx4 v[178:179], off
	v_lshl_add_u64 v[178:179], s[72:73], 0, v[172:173]
	s_mov_b32 m0, s77
	s_nop 0
	global_load_lds_dwordx4 v[178:179], off
	s_mov_b32 m0, s78
	s_nop 0
	global_load_lds_dwordx4 v[180:181], off
	s_waitcnt vmcnt(8)
	s_waitcnt lgkmcnt(0)
	s_setprio 1
	s_barrier
	v_mfma_f32_16x16x32_bf16 v[64:67], v[132:135], v[164:167], v[64:67]
	v_mfma_f32_16x16x32_bf16 v[60:63], v[140:143], v[164:167], v[60:63]
	v_mfma_f32_16x16x32_bf16 v[48:51], v[132:135], v[192:195], v[48:51]
	v_mfma_f32_16x16x32_bf16 v[44:47], v[140:143], v[192:195], v[44:47]
	v_mfma_f32_16x16x32_bf16 v[32:35], v[132:135], v[200:203], v[32:35]
	v_mfma_f32_16x16x32_bf16 v[28:31], v[140:143], v[200:203], v[28:31]
	v_mfma_f32_16x16x32_bf16 v[16:19], v[132:135], v[208:211], v[16:19]
	v_mfma_f32_16x16x32_bf16 v[12:15], v[140:143], v[208:211], v[12:15]
	v_mfma_f32_16x16x32_bf16 v[64:67], v[136:139], v[188:191], v[64:67]
	v_mfma_f32_16x16x32_bf16 v[60:63], v[144:147], v[188:191], v[60:63]
	v_mfma_f32_16x16x32_bf16 v[48:51], v[136:139], v[196:199], v[48:51]
	v_mfma_f32_16x16x32_bf16 v[44:47], v[144:147], v[196:199], v[44:47]
	v_mfma_f32_16x16x32_bf16 v[32:35], v[136:139], v[204:207], v[32:35]
	v_mfma_f32_16x16x32_bf16 v[28:31], v[144:147], v[204:207], v[28:31]
	v_mfma_f32_16x16x32_bf16 v[16:19], v[136:139], v[212:215], v[16:19]
	v_mfma_f32_16x16x32_bf16 v[12:15], v[144:147], v[212:215], v[12:15]
	v_mfma_f32_16x16x32_bf16 v[56:59], v[148:151], v[164:167], v[56:59]
	v_mfma_f32_16x16x32_bf16 v[52:55], v[156:159], v[164:167], v[52:55]
	v_mfma_f32_16x16x32_bf16 v[40:43], v[148:151], v[192:195], v[40:43]
	v_mfma_f32_16x16x32_bf16 v[36:39], v[156:159], v[192:195], v[36:39]
	v_mfma_f32_16x16x32_bf16 v[24:27], v[148:151], v[200:203], v[24:27]
	v_mfma_f32_16x16x32_bf16 v[20:23], v[156:159], v[200:203], v[20:23]
	v_mfma_f32_16x16x32_bf16 v[8:11], v[148:151], v[208:211], v[8:11]
	v_mfma_f32_16x16x32_bf16 v[4:7], v[156:159], v[208:211], v[4:7]
	v_mfma_f32_16x16x32_bf16 v[56:59], v[152:155], v[188:191], v[56:59]
	v_mfma_f32_16x16x32_bf16 v[52:55], v[160:163], v[188:191], v[52:55]
	v_mfma_f32_16x16x32_bf16 v[40:43], v[152:155], v[196:199], v[40:43]
	v_mfma_f32_16x16x32_bf16 v[36:39], v[160:163], v[196:199], v[36:39]
	v_mfma_f32_16x16x32_bf16 v[24:27], v[152:155], v[204:207], v[24:27]
	v_mfma_f32_16x16x32_bf16 v[20:23], v[160:163], v[204:207], v[20:23]
	v_mfma_f32_16x16x32_bf16 v[8:11], v[152:155], v[212:215], v[8:11]
	v_mfma_f32_16x16x32_bf16 v[4:7], v[160:163], v[212:215], v[4:7]
	s_barrier
	s_setprio 0
	s_add_i32 s11, 0, 0x18000
	s_add_i32 s94, 0, 0x1c000
	v_add_u32_e32 v144, s11, v244
	v_add_u32_e32 v160, s94, v244
	ds_read_b128 v[132:135], v144
	ds_read_b128 v[136:139], v144 offset:1024
	ds_read_b128 v[140:143], v144 offset:2048
	ds_read_b128 v[144:147], v144 offset:3072
	ds_read_b128 v[148:151], v160
	ds_read_b128 v[152:155], v160 offset:1024
	ds_read_b128 v[156:159], v160 offset:2048
	ds_read_b128 v[160:163], v160 offset:3072
	s_add_u32 s16, s72, 0x80000
	s_addc_u32 s17, s73, 0
	s_mov_b32 m0, s95
	v_lshl_add_u64 v[182:183], s[16:17], 0, v[172:173]
	ds_read_b128 v[164:167], v246 offset:32768
	ds_read_b128 v[188:191], v246 offset:33792
	ds_read_b128 v[192:195], v246 offset:34816
	ds_read_b128 v[196:199], v246 offset:35840
	ds_read_b128 v[200:203], v246 offset:36864
	ds_read_b128 v[204:207], v246 offset:37888
	ds_read_b128 v[208:211], v246 offset:38912
	ds_read_b128 v[212:215], v246 offset:39936
	global_load_lds_dwordx4 v[182:183], off
	v_lshl_add_u64 v[182:183], s[16:17], 0, v[170:171]
	s_mov_b32 m0, s68
	s_nop 0
	global_load_lds_dwordx4 v[182:183], off
	s_waitcnt vmcnt(8)
	s_waitcnt lgkmcnt(0)
	s_setprio 1
	s_barrier
	v_mfma_f32_16x16x32_bf16 v[128:131], v[132:135], v[164:167], v[128:131]
	v_mfma_f32_16x16x32_bf16 v[124:127], v[140:143], v[164:167], v[124:127]
	v_mfma_f32_16x16x32_bf16 v[112:115], v[132:135], v[192:195], v[112:115]
	v_mfma_f32_16x16x32_bf16 v[108:111], v[140:143], v[192:195], v[108:111]
	v_mfma_f32_16x16x32_bf16 v[96:99], v[132:135], v[200:203], v[96:99]
	v_mfma_f32_16x16x32_bf16 v[92:95], v[140:143], v[200:203], v[92:95]
	v_mfma_f32_16x16x32_bf16 v[80:83], v[132:135], v[208:211], v[80:83]
	v_mfma_f32_16x16x32_bf16 v[76:79], v[140:143], v[208:211], v[76:79]
	v_mfma_f32_16x16x32_bf16 v[128:131], v[136:139], v[188:191], v[128:131]
	v_mfma_f32_16x16x32_bf16 v[124:127], v[144:147], v[188:191], v[124:127]
	v_mfma_f32_16x16x32_bf16 v[112:115], v[136:139], v[196:199], v[112:115]
	v_mfma_f32_16x16x32_bf16 v[108:111], v[144:147], v[196:199], v[108:111]
	v_mfma_f32_16x16x32_bf16 v[96:99], v[136:139], v[204:207], v[96:99]
	v_mfma_f32_16x16x32_bf16 v[92:95], v[144:147], v[204:207], v[92:95]
	v_mfma_f32_16x16x32_bf16 v[80:83], v[136:139], v[212:215], v[80:83]
	v_mfma_f32_16x16x32_bf16 v[76:79], v[144:147], v[212:215], v[76:79]
	v_mfma_f32_16x16x32_bf16 v[120:123], v[148:151], v[164:167], v[120:123]
	v_mfma_f32_16x16x32_bf16 v[116:119], v[156:159], v[164:167], v[116:119]
	v_mfma_f32_16x16x32_bf16 v[104:107], v[148:151], v[192:195], v[104:107]
	v_mfma_f32_16x16x32_bf16 v[100:103], v[156:159], v[192:195], v[100:103]
	v_mfma_f32_16x16x32_bf16 v[88:91], v[148:151], v[200:203], v[88:91]
	v_mfma_f32_16x16x32_bf16 v[84:87], v[156:159], v[200:203], v[84:87]
	v_mfma_f32_16x16x32_bf16 v[72:75], v[148:151], v[208:211], v[72:75]
	v_mfma_f32_16x16x32_bf16 v[68:71], v[156:159], v[208:211], v[68:71]
	v_mfma_f32_16x16x32_bf16 v[120:123], v[152:155], v[188:191], v[120:123]
	v_mfma_f32_16x16x32_bf16 v[116:119], v[160:163], v[188:191], v[116:119]
	v_mfma_f32_16x16x32_bf16 v[104:107], v[152:155], v[196:199], v[104:107]
	v_mfma_f32_16x16x32_bf16 v[100:103], v[160:163], v[196:199], v[100:103]
	v_mfma_f32_16x16x32_bf16 v[88:91], v[152:155], v[204:207], v[88:91]
	v_mfma_f32_16x16x32_bf16 v[84:87], v[160:163], v[204:207], v[84:87]
	v_mfma_f32_16x16x32_bf16 v[72:75], v[152:155], v[212:215], v[72:75]
	v_mfma_f32_16x16x32_bf16 v[68:71], v[160:163], v[212:215], v[68:71]
	s_barrier
	s_setprio 0
	s_add_i32 s11, s11, s74
	v_lshl_add_u64 v[174:175], v[174:175], 0, s[24:25]
	s_mov_b32 m0, s11
	ds_read_b128 v[164:167], v246 offset:49152
	ds_read_b128 v[188:191], v246 offset:50176
	ds_read_b128 v[192:195], v246 offset:51200
	ds_read_b128 v[196:199], v246 offset:52224
	ds_read_b128 v[200:203], v246 offset:53248
	ds_read_b128 v[204:207], v246 offset:54272
	ds_read_b128 v[208:211], v246 offset:55296
	ds_read_b128 v[212:215], v246 offset:56320
	global_load_lds_dwordx4 v[174:175], off
	s_add_i32 m0, s11, 0x2000
	s_add_u32 s16, s28, 0x20080
	v_lshl_add_u64 v[174:175], v[176:177], 0, s[24:25]
	s_addc_u32 s17, s29, 0
	s_add_i32 s11, s94, s74
	global_load_lds_dwordx4 v[174:175], off
	v_lshl_add_u64 v[174:175], s[16:17], 0, v[2:3]
	s_mov_b32 m0, s11
	s_nop 0
	global_load_lds_dwordx4 v[174:175], off
	v_lshl_add_u64 v[174:175], s[16:17], 0, v[168:169]
	s_add_i32 m0, s11, 0x2000
	s_nop 0
	global_load_lds_dwordx4 v[174:175], off
	v_lshl_add_u64 v[174:175], v[178:179], 0, s[24:25]
	s_mov_b32 m0, s96
	s_nop 0
	global_load_lds_dwordx4 v[174:175], off
	v_lshl_add_u64 v[174:175], v[180:181], 0, s[24:25]
	s_mov_b32 m0, s3
	s_nop 0
	global_load_lds_dwordx4 v[174:175], off
	s_waitcnt vmcnt(8)
	s_waitcnt lgkmcnt(0)
	s_setprio 1
	s_barrier
	v_mfma_f32_16x16x32_bf16 v[64:67], v[132:135], v[164:167], v[64:67]
	v_mfma_f32_16x16x32_bf16 v[60:63], v[140:143], v[164:167], v[60:63]
	v_mfma_f32_16x16x32_bf16 v[48:51], v[132:135], v[192:195], v[48:51]
	v_mfma_f32_16x16x32_bf16 v[44:47], v[140:143], v[192:195], v[44:47]
	v_mfma_f32_16x16x32_bf16 v[32:35], v[132:135], v[200:203], v[32:35]
	v_mfma_f32_16x16x32_bf16 v[28:31], v[140:143], v[200:203], v[28:31]
	v_mfma_f32_16x16x32_bf16 v[16:19], v[132:135], v[208:211], v[16:19]
	v_mfma_f32_16x16x32_bf16 v[12:15], v[140:143], v[208:211], v[12:15]
	v_mfma_f32_16x16x32_bf16 v[64:67], v[136:139], v[188:191], v[64:67]
	v_mfma_f32_16x16x32_bf16 v[60:63], v[144:147], v[188:191], v[60:63]
	v_mfma_f32_16x16x32_bf16 v[48:51], v[136:139], v[196:199], v[48:51]
	v_mfma_f32_16x16x32_bf16 v[44:47], v[144:147], v[196:199], v[44:47]
	v_mfma_f32_16x16x32_bf16 v[32:35], v[136:139], v[204:207], v[32:35]
	v_mfma_f32_16x16x32_bf16 v[28:31], v[144:147], v[204:207], v[28:31]
	v_mfma_f32_16x16x32_bf16 v[16:19], v[136:139], v[212:215], v[16:19]
	v_mfma_f32_16x16x32_bf16 v[12:15], v[144:147], v[212:215], v[12:15]
	v_mfma_f32_16x16x32_bf16 v[56:59], v[148:151], v[164:167], v[56:59]
	v_mfma_f32_16x16x32_bf16 v[52:55], v[156:159], v[164:167], v[52:55]
	v_mfma_f32_16x16x32_bf16 v[40:43], v[148:151], v[192:195], v[40:43]
	v_mfma_f32_16x16x32_bf16 v[36:39], v[156:159], v[192:195], v[36:39]
	v_mfma_f32_16x16x32_bf16 v[24:27], v[148:151], v[200:203], v[24:27]
	v_mfma_f32_16x16x32_bf16 v[20:23], v[156:159], v[200:203], v[20:23]
	v_mfma_f32_16x16x32_bf16 v[8:11], v[148:151], v[208:211], v[8:11]
	v_mfma_f32_16x16x32_bf16 v[4:7], v[156:159], v[208:211], v[4:7]
	v_mfma_f32_16x16x32_bf16 v[56:59], v[152:155], v[188:191], v[56:59]
	v_mfma_f32_16x16x32_bf16 v[52:55], v[160:163], v[188:191], v[52:55]
	v_mfma_f32_16x16x32_bf16 v[40:43], v[152:155], v[196:199], v[40:43]
	v_mfma_f32_16x16x32_bf16 v[36:39], v[160:163], v[196:199], v[36:39]
	v_mfma_f32_16x16x32_bf16 v[24:27], v[152:155], v[204:207], v[24:27]
	v_mfma_f32_16x16x32_bf16 v[20:23], v[160:163], v[204:207], v[20:23]
	v_mfma_f32_16x16x32_bf16 v[8:11], v[152:155], v[212:215], v[8:11]
	v_mfma_f32_16x16x32_bf16 v[4:7], v[160:163], v[212:215], v[4:7]
	s_barrier
	s_setprio 0
	s_add_i32 s10, s10, 2
	s_add_u32 vcc_lo, vcc_lo, 0x100
	s_addc_u32 vcc_hi, vcc_hi, 0
	s_add_u32 s48, s48, 0x100
	s_addc_u32 s49, s49, 0
	s_cmp_gt_u32 s10, 29
	s_cbranch_scc0 .LBB0_790
	v_readlane_b32 s10, v252, 2
	v_readlane_b32 s11, v252, 3
	s_and_b64 vcc, exec, s[10:11]
	s_cbranch_vccz .LBB0_793
	s_barrier

.LBB0_870:
	s_add_u32 s16, s44, 0xfff80080
	s_addc_u32 s17, s45, -1
	s_add_i32 s94, 0, 0x10000
	s_cmp_eq_u32 vcc_lo, 28
	s_cselect_b32 s47, s37, s17
	s_cselect_b32 s46, s88, s16
	s_cselect_b32 s29, s27, s96
	s_cselect_b32 s28, s89, s91
	s_add_i32 s95, 0, 0x14000
	v_add_u32_e32 v144, s94, v227
	v_add_u32_e32 v170, s95, v227
	ds_read_b128 v[132:135], v144
	ds_read_b128 v[136:139], v144 offset:1024
	ds_read_b128 v[140:143], v144 offset:2048
	ds_read_b128 v[144:147], v144 offset:3072
	ds_read_b128 v[148:151], v170
	ds_read_b128 v[152:155], v170 offset:1024
	ds_read_b128 v[166:169], v170 offset:2048
	ds_read_b128 v[170:173], v170 offset:3072
	v_lshl_add_u64 v[174:175], s[44:45], 0, v[162:163]
	s_add_i32 m0, s48, 0xc000
	ds_read_b128 v[184:187], v229
	ds_read_b128 v[188:191], v229 offset:1024
	ds_read_b128 v[192:195], v229 offset:2048
	ds_read_b128 v[196:199], v229 offset:3072
	ds_read_b128 v[200:203], v229 offset:4096
	ds_read_b128 v[204:207], v229 offset:5120
	ds_read_b128 v[208:211], v229 offset:6144
	ds_read_b128 v[212:215], v229 offset:7168
	global_load_lds_dwordx4 v[174:175], off
	v_lshl_add_u64 v[174:175], s[44:45], 0, v[164:165]
	s_add_i32 m0, s48, 0xe000
	s_nop 0
	global_load_lds_dwordx4 v[174:175], off
	s_waitcnt vmcnt(8)
	s_waitcnt lgkmcnt(0)
	s_setprio 1
	s_barrier
	v_mfma_f32_16x16x32_bf16 v[128:131], v[132:135], v[184:187], v[128:131]
	v_mfma_f32_16x16x32_bf16 v[124:127], v[140:143], v[184:187], v[124:127]
	v_mfma_f32_16x16x32_bf16 v[112:115], v[132:135], v[192:195], v[112:115]
	v_mfma_f32_16x16x32_bf16 v[108:111], v[140:143], v[192:195], v[108:111]
	v_mfma_f32_16x16x32_bf16 v[96:99], v[132:135], v[200:203], v[96:99]
	v_mfma_f32_16x16x32_bf16 v[92:95], v[140:143], v[200:203], v[92:95]
	v_mfma_f32_16x16x32_bf16 v[80:83], v[132:135], v[208:211], v[80:83]
	v_mfma_f32_16x16x32_bf16 v[76:79], v[140:143], v[208:211], v[76:79]
	v_mfma_f32_16x16x32_bf16 v[128:131], v[136:139], v[188:191], v[128:131]
	v_mfma_f32_16x16x32_bf16 v[124:127], v[144:147], v[188:191], v[124:127]
	v_mfma_f32_16x16x32_bf16 v[112:115], v[136:139], v[196:199], v[112:115]
	v_mfma_f32_16x16x32_bf16 v[108:111], v[144:147], v[196:199], v[108:111]
	v_mfma_f32_16x16x32_bf16 v[96:99], v[136:139], v[204:207], v[96:99]
	v_mfma_f32_16x16x32_bf16 v[92:95], v[144:147], v[204:207], v[92:95]
	v_mfma_f32_16x16x32_bf16 v[80:83], v[136:139], v[212:215], v[80:83]
	v_mfma_f32_16x16x32_bf16 v[76:79], v[144:147], v[212:215], v[76:79]
	v_mfma_f32_16x16x32_bf16 v[120:123], v[148:151], v[184:187], v[120:123]
	v_mfma_f32_16x16x32_bf16 v[116:119], v[166:169], v[184:187], v[116:119]
	v_mfma_f32_16x16x32_bf16 v[104:107], v[148:151], v[192:195], v[104:107]
	v_mfma_f32_16x16x32_bf16 v[100:103], v[166:169], v[192:195], v[100:103]
	v_mfma_f32_16x16x32_bf16 v[88:91], v[148:151], v[200:203], v[88:91]
	v_mfma_f32_16x16x32_bf16 v[84:87], v[166:169], v[200:203], v[84:87]
	v_mfma_f32_16x16x32_bf16 v[72:75], v[148:151], v[208:211], v[72:75]
	v_mfma_f32_16x16x32_bf16 v[68:71], v[166:169], v[208:211], v[68:71]
	v_mfma_f32_16x16x32_bf16 v[120:123], v[152:155], v[188:191], v[120:123]
	v_mfma_f32_16x16x32_bf16 v[116:119], v[170:173], v[188:191], v[116:119]
	v_mfma_f32_16x16x32_bf16 v[104:107], v[152:155], v[196:199], v[104:107]
	v_mfma_f32_16x16x32_bf16 v[100:103], v[170:173], v[196:199], v[100:103]
	v_mfma_f32_16x16x32_bf16 v[88:91], v[152:155], v[204:207], v[88:91]
	v_mfma_f32_16x16x32_bf16 v[84:87], v[170:173], v[204:207], v[84:87]
	v_mfma_f32_16x16x32_bf16 v[72:75], v[152:155], v[212:215], v[72:75]
	v_mfma_f32_16x16x32_bf16 v[68:71], v[170:173], v[212:215], v[68:71]
	s_barrier
	s_setprio 0
	s_add_i32 s16, s94, s33
	v_lshl_add_u64 v[174:175], s[28:29], 0, v[2:3]
	s_mov_b32 m0, s16
	ds_read_b128 v[184:187], v229 offset:16384
	ds_read_b128 v[188:191], v229 offset:17408
	ds_read_b128 v[192:195], v229 offset:18432
	ds_read_b128 v[196:199], v229 offset:19456
	ds_read_b128 v[200:203], v229 offset:20480
	ds_read_b128 v[204:207], v229 offset:21504
	ds_read_b128 v[208:211], v229 offset:22528
	ds_read_b128 v[212:215], v229 offset:23552
	global_load_lds_dwordx4 v[174:175], off
	s_add_i32 m0, s16, 0x2000
	s_add_u32 s16, s28, 0x80000
	v_lshl_add_u64 v[176:177], s[28:29], 0, v[156:157]
	s_addc_u32 s17, s29, 0
	s_add_i32 s94, s95, s33
	global_load_lds_dwordx4 v[176:177], off
	v_lshl_add_u64 v[178:179], s[16:17], 0, v[2:3]
	s_mov_b32 m0, s94
	v_lshl_add_u64 v[180:181], s[46:47], 0, v[158:159]
	global_load_lds_dwordx4 v[178:179], off
	v_lshl_add_u64 v[178:179], s[16:17], 0, v[156:157]
	s_add_i32 m0, s94, 0x2000
	s_nop 0
	global_load_lds_dwordx4 v[178:179], off
	v_lshl_add_u64 v[178:179], s[46:47], 0, v[160:161]
	s_mov_b32 m0, s48
	s_nop 0
	global_load_lds_dwordx4 v[178:179], off
	s_mov_b32 m0, s49
	s_nop 0
	global_load_lds_dwordx4 v[180:181], off
	s_waitcnt vmcnt(8)
	s_waitcnt lgkmcnt(0)
	s_setprio 1
	s_barrier
	v_mfma_f32_16x16x32_bf16 v[64:67], v[132:135], v[184:187], v[64:67]
	v_mfma_f32_16x16x32_bf16 v[60:63], v[140:143], v[184:187], v[60:63]
	v_mfma_f32_16x16x32_bf16 v[48:51], v[132:135], v[192:195], v[48:51]
	v_mfma_f32_16x16x32_bf16 v[44:47], v[140:143], v[192:195], v[44:47]
	v_mfma_f32_16x16x32_bf16 v[32:35], v[132:135], v[200:203], v[32:35]
	v_mfma_f32_16x16x32_bf16 v[28:31], v[140:143], v[200:203], v[28:31]
	v_mfma_f32_16x16x32_bf16 v[16:19], v[132:135], v[208:211], v[16:19]
	v_mfma_f32_16x16x32_bf16 v[12:15], v[140:143], v[208:211], v[12:15]
	v_mfma_f32_16x16x32_bf16 v[64:67], v[136:139], v[188:191], v[64:67]
	v_mfma_f32_16x16x32_bf16 v[60:63], v[144:147], v[188:191], v[60:63]
	v_mfma_f32_16x16x32_bf16 v[48:51], v[136:139], v[196:199], v[48:51]
	v_mfma_f32_16x16x32_bf16 v[44:47], v[144:147], v[196:199], v[44:47]
	v_mfma_f32_16x16x32_bf16 v[32:35], v[136:139], v[204:207], v[32:35]
	v_mfma_f32_16x16x32_bf16 v[28:31], v[144:147], v[204:207], v[28:31]
	v_mfma_f32_16x16x32_bf16 v[16:19], v[136:139], v[212:215], v[16:19]
	v_mfma_f32_16x16x32_bf16 v[12:15], v[144:147], v[212:215], v[12:15]
	v_mfma_f32_16x16x32_bf16 v[56:59], v[148:151], v[184:187], v[56:59]
	v_mfma_f32_16x16x32_bf16 v[52:55], v[166:169], v[184:187], v[52:55]
	v_mfma_f32_16x16x32_bf16 v[40:43], v[148:151], v[192:195], v[40:43]
	v_mfma_f32_16x16x32_bf16 v[36:39], v[166:169], v[192:195], v[36:39]
	v_mfma_f32_16x16x32_bf16 v[24:27], v[148:151], v[200:203], v[24:27]
	v_mfma_f32_16x16x32_bf16 v[20:23], v[166:169], v[200:203], v[20:23]
	v_mfma_f32_16x16x32_bf16 v[8:11], v[148:151], v[208:211], v[8:11]
	v_mfma_f32_16x16x32_bf16 v[4:7], v[166:169], v[208:211], v[4:7]
	v_mfma_f32_16x16x32_bf16 v[56:59], v[152:155], v[188:191], v[56:59]
	v_mfma_f32_16x16x32_bf16 v[52:55], v[170:173], v[188:191], v[52:55]
	v_mfma_f32_16x16x32_bf16 v[40:43], v[152:155], v[196:199], v[40:43]
	v_mfma_f32_16x16x32_bf16 v[36:39], v[170:173], v[196:199], v[36:39]
	v_mfma_f32_16x16x32_bf16 v[24:27], v[152:155], v[204:207], v[24:27]
	v_mfma_f32_16x16x32_bf16 v[20:23], v[170:173], v[204:207], v[20:23]
	v_mfma_f32_16x16x32_bf16 v[8:11], v[152:155], v[212:215], v[8:11]
	v_mfma_f32_16x16x32_bf16 v[4:7], v[170:173], v[212:215], v[4:7]
	s_barrier
	s_setprio 0
	s_add_i32 s94, 0, 0x18000
	s_add_i32 s95, 0, 0x1c000
	v_add_u32_e32 v144, s94, v227
	v_add_u32_e32 v170, s95, v227
	ds_read_b128 v[132:135], v144
	ds_read_b128 v[136:139], v144 offset:1024
	ds_read_b128 v[140:143], v144 offset:2048
	ds_read_b128 v[144:147], v144 offset:3072
	ds_read_b128 v[148:151], v170
	ds_read_b128 v[152:155], v170 offset:1024
	ds_read_b128 v[166:169], v170 offset:2048
	ds_read_b128 v[170:173], v170 offset:3072
	s_add_u32 s16, s46, 0x80000
	s_addc_u32 s17, s47, 0
	s_mov_b32 m0, s50
	v_lshl_add_u64 v[182:183], s[16:17], 0, v[160:161]
	ds_read_b128 v[184:187], v229 offset:32768
	ds_read_b128 v[188:191], v229 offset:33792
	ds_read_b128 v[192:195], v229 offset:34816
	ds_read_b128 v[196:199], v229 offset:35840
	ds_read_b128 v[200:203], v229 offset:36864
	ds_read_b128 v[204:207], v229 offset:37888
	ds_read_b128 v[208:211], v229 offset:38912
	ds_read_b128 v[212:215], v229 offset:39936
	global_load_lds_dwordx4 v[182:183], off
	v_lshl_add_u64 v[182:183], s[16:17], 0, v[158:159]
	s_mov_b32 m0, s51
	s_nop 0
	global_load_lds_dwordx4 v[182:183], off
	s_waitcnt vmcnt(8)
	s_waitcnt lgkmcnt(0)
	s_setprio 1
	s_barrier
	v_mfma_f32_16x16x32_bf16 v[128:131], v[132:135], v[184:187], v[128:131]
	v_mfma_f32_16x16x32_bf16 v[124:127], v[140:143], v[184:187], v[124:127]
	v_mfma_f32_16x16x32_bf16 v[112:115], v[132:135], v[192:195], v[112:115]
	v_mfma_f32_16x16x32_bf16 v[108:111], v[140:143], v[192:195], v[108:111]
	v_mfma_f32_16x16x32_bf16 v[96:99], v[132:135], v[200:203], v[96:99]
	v_mfma_f32_16x16x32_bf16 v[92:95], v[140:143], v[200:203], v[92:95]
	v_mfma_f32_16x16x32_bf16 v[80:83], v[132:135], v[208:211], v[80:83]
	v_mfma_f32_16x16x32_bf16 v[76:79], v[140:143], v[208:211], v[76:79]
	v_mfma_f32_16x16x32_bf16 v[128:131], v[136:139], v[188:191], v[128:131]
	v_mfma_f32_16x16x32_bf16 v[124:127], v[144:147], v[188:191], v[124:127]
	v_mfma_f32_16x16x32_bf16 v[112:115], v[136:139], v[196:199], v[112:115]
	v_mfma_f32_16x16x32_bf16 v[108:111], v[144:147], v[196:199], v[108:111]
	v_mfma_f32_16x16x32_bf16 v[96:99], v[136:139], v[204:207], v[96:99]
	v_mfma_f32_16x16x32_bf16 v[92:95], v[144:147], v[204:207], v[92:95]
	v_mfma_f32_16x16x32_bf16 v[80:83], v[136:139], v[212:215], v[80:83]
	v_mfma_f32_16x16x32_bf16 v[76:79], v[144:147], v[212:215], v[76:79]
	v_mfma_f32_16x16x32_bf16 v[120:123], v[148:151], v[184:187], v[120:123]
	v_mfma_f32_16x16x32_bf16 v[116:119], v[166:169], v[184:187], v[116:119]
	v_mfma_f32_16x16x32_bf16 v[104:107], v[148:151], v[192:195], v[104:107]
	v_mfma_f32_16x16x32_bf16 v[100:103], v[166:169], v[192:195], v[100:103]
	v_mfma_f32_16x16x32_bf16 v[88:91], v[148:151], v[200:203], v[88:91]
	v_mfma_f32_16x16x32_bf16 v[84:87], v[166:169], v[200:203], v[84:87]
	v_mfma_f32_16x16x32_bf16 v[72:75], v[148:151], v[208:211], v[72:75]
	v_mfma_f32_16x16x32_bf16 v[68:71], v[166:169], v[208:211], v[68:71]
	v_mfma_f32_16x16x32_bf16 v[120:123], v[152:155], v[188:191], v[120:123]
	v_mfma_f32_16x16x32_bf16 v[116:119], v[170:173], v[188:191], v[116:119]
	v_mfma_f32_16x16x32_bf16 v[104:107], v[152:155], v[196:199], v[104:107]
	v_mfma_f32_16x16x32_bf16 v[100:103], v[170:173], v[196:199], v[100:103]
	v_mfma_f32_16x16x32_bf16 v[88:91], v[152:155], v[204:207], v[88:91]
	v_mfma_f32_16x16x32_bf16 v[84:87], v[170:173], v[204:207], v[84:87]
	v_mfma_f32_16x16x32_bf16 v[72:75], v[152:155], v[212:215], v[72:75]
	v_mfma_f32_16x16x32_bf16 v[68:71], v[170:173], v[212:215], v[68:71]
	s_barrier
	s_setprio 0
	s_add_i32 s16, s94, s33
	v_lshl_add_u64 v[174:175], v[174:175], 0, s[24:25]
	s_mov_b32 m0, s16
	ds_read_b128 v[184:187], v229 offset:49152
	ds_read_b128 v[188:191], v229 offset:50176
	ds_read_b128 v[192:195], v229 offset:51200
	ds_read_b128 v[196:199], v229 offset:52224
	ds_read_b128 v[200:203], v229 offset:53248
	ds_read_b128 v[204:207], v229 offset:54272
	ds_read_b128 v[208:211], v229 offset:55296
	ds_read_b128 v[212:215], v229 offset:56320
	global_load_lds_dwordx4 v[174:175], off
	s_add_i32 m0, s16, 0x2000
	s_add_u32 s16, s28, 0x80080
	v_lshl_add_u64 v[174:175], v[176:177], 0, s[24:25]
	s_addc_u32 s17, s29, 0
	s_add_i32 s28, s95, s33
	global_load_lds_dwordx4 v[174:175], off
	v_lshl_add_u64 v[174:175], s[16:17], 0, v[2:3]
	s_mov_b32 m0, s28
	s_nop 0
	global_load_lds_dwordx4 v[174:175], off
	v_lshl_add_u64 v[174:175], s[16:17], 0, v[156:157]
	s_add_i32 m0, s28, 0x2000
	s_nop 0
	global_load_lds_dwordx4 v[174:175], off
	v_lshl_add_u64 v[174:175], v[178:179], 0, s[24:25]
	s_mov_b32 m0, s72
	s_nop 0
	global_load_lds_dwordx4 v[174:175], off
	v_lshl_add_u64 v[174:175], v[180:181], 0, s[24:25]
	s_mov_b32 m0, s73
	s_nop 0
	global_load_lds_dwordx4 v[174:175], off
	s_waitcnt vmcnt(8)
	s_waitcnt lgkmcnt(0)
	s_setprio 1
	s_barrier
	v_mfma_f32_16x16x32_bf16 v[64:67], v[132:135], v[184:187], v[64:67]
	v_mfma_f32_16x16x32_bf16 v[60:63], v[140:143], v[184:187], v[60:63]
	v_mfma_f32_16x16x32_bf16 v[48:51], v[132:135], v[192:195], v[48:51]
	v_mfma_f32_16x16x32_bf16 v[44:47], v[140:143], v[192:195], v[44:47]
	v_mfma_f32_16x16x32_bf16 v[32:35], v[132:135], v[200:203], v[32:35]
	v_mfma_f32_16x16x32_bf16 v[28:31], v[140:143], v[200:203], v[28:31]
	v_mfma_f32_16x16x32_bf16 v[16:19], v[132:135], v[208:211], v[16:19]
	v_mfma_f32_16x16x32_bf16 v[12:15], v[140:143], v[208:211], v[12:15]
	v_mfma_f32_16x16x32_bf16 v[64:67], v[136:139], v[188:191], v[64:67]
	v_mfma_f32_16x16x32_bf16 v[60:63], v[144:147], v[188:191], v[60:63]
	v_mfma_f32_16x16x32_bf16 v[48:51], v[136:139], v[196:199], v[48:51]
	v_mfma_f32_16x16x32_bf16 v[44:47], v[144:147], v[196:199], v[44:47]
	v_mfma_f32_16x16x32_bf16 v[32:35], v[136:139], v[204:207], v[32:35]
	v_mfma_f32_16x16x32_bf16 v[28:31], v[144:147], v[204:207], v[28:31]
	v_mfma_f32_16x16x32_bf16 v[16:19], v[136:139], v[212:215], v[16:19]
	v_mfma_f32_16x16x32_bf16 v[12:15], v[144:147], v[212:215], v[12:15]
	v_mfma_f32_16x16x32_bf16 v[56:59], v[148:151], v[184:187], v[56:59]
	v_mfma_f32_16x16x32_bf16 v[52:55], v[166:169], v[184:187], v[52:55]
	v_mfma_f32_16x16x32_bf16 v[40:43], v[148:151], v[192:195], v[40:43]
	v_mfma_f32_16x16x32_bf16 v[36:39], v[166:169], v[192:195], v[36:39]
	v_mfma_f32_16x16x32_bf16 v[24:27], v[148:151], v[200:203], v[24:27]
	v_mfma_f32_16x16x32_bf16 v[20:23], v[166:169], v[200:203], v[20:23]
	v_mfma_f32_16x16x32_bf16 v[8:11], v[148:151], v[208:211], v[8:11]
	v_mfma_f32_16x16x32_bf16 v[4:7], v[166:169], v[208:211], v[4:7]
	v_mfma_f32_16x16x32_bf16 v[56:59], v[152:155], v[188:191], v[56:59]
	v_mfma_f32_16x16x32_bf16 v[52:55], v[170:173], v[188:191], v[52:55]
	v_mfma_f32_16x16x32_bf16 v[40:43], v[152:155], v[196:199], v[40:43]
	v_mfma_f32_16x16x32_bf16 v[36:39], v[170:173], v[196:199], v[36:39]
	v_mfma_f32_16x16x32_bf16 v[24:27], v[152:155], v[204:207], v[24:27]
	v_mfma_f32_16x16x32_bf16 v[20:23], v[170:173], v[204:207], v[20:23]
	v_mfma_f32_16x16x32_bf16 v[8:11], v[152:155], v[212:215], v[8:11]
	v_mfma_f32_16x16x32_bf16 v[4:7], v[170:173], v[212:215], v[4:7]
	s_barrier
	s_setprio 0
	s_add_i32 vcc_lo, vcc_lo, 2
	s_add_u32 s44, s44, 0x100
	s_addc_u32 s45, s45, 0
	s_add_u32 s91, s91, 0x100
	s_addc_u32 s96, s96, 0
	s_cmp_gt_u32 vcc_lo, 29
	s_cbranch_scc0 .LBB0_870
	s_and_b64 vcc, exec, s[22:23]
	s_cbranch_vccz .LBB0_873
	s_barrier

.LBB0_1035:
	s_add_u32 s46, s50, 0x100
	s_addc_u32 s47, s51, 0
	s_add_i32 s16, 0, 0x10000
	s_cmpk_eq_i32 s48, 0x54
	s_cselect_b32 s73, s23, s47
	s_cselect_b32 s72, s22, s46
	s_cselect_b32 s29, s27, vcc_hi
	s_cselect_b32 s28, s26, vcc_lo
	s_add_i32 s49, 0, 0x14000
	v_add_u32_e32 v144, s16, v244
	v_add_u32_e32 v160, s49, v244
	ds_read_b128 v[132:135], v144
	ds_read_b128 v[136:139], v144 offset:1024
	ds_read_b128 v[140:143], v144 offset:2048
	ds_read_b128 v[144:147], v144 offset:3072
	ds_read_b128 v[148:151], v160
	ds_read_b128 v[152:155], v160 offset:1024
	ds_read_b128 v[156:159], v160 offset:2048
	ds_read_b128 v[160:163], v160 offset:3072
	v_lshl_add_u64 v[174:175], s[50:51], 0, v[184:185]
	s_add_i32 m0, s77, 0xc000
	ds_read_b128 v[164:167], v246
	ds_read_b128 v[188:191], v246 offset:1024
	ds_read_b128 v[192:195], v246 offset:2048
	ds_read_b128 v[196:199], v246 offset:3072
	ds_read_b128 v[200:203], v246 offset:4096
	ds_read_b128 v[204:207], v246 offset:5120
	ds_read_b128 v[208:211], v246 offset:6144
	ds_read_b128 v[212:215], v246 offset:7168
	global_load_lds_dwordx4 v[174:175], off
	v_lshl_add_u64 v[174:175], s[50:51], 0, v[186:187]
	s_add_i32 m0, s77, 0xe000
	s_nop 0
	global_load_lds_dwordx4 v[174:175], off
	s_waitcnt vmcnt(8)
	s_waitcnt lgkmcnt(0)
	s_setprio 1
	s_barrier
	v_mfma_f32_16x16x32_bf16 v[128:131], v[132:135], v[164:167], v[128:131]
	v_mfma_f32_16x16x32_bf16 v[124:127], v[140:143], v[164:167], v[124:127]
	v_mfma_f32_16x16x32_bf16 v[112:115], v[132:135], v[192:195], v[112:115]
	v_mfma_f32_16x16x32_bf16 v[108:111], v[140:143], v[192:195], v[108:111]
	v_mfma_f32_16x16x32_bf16 v[96:99], v[132:135], v[200:203], v[96:99]
	v_mfma_f32_16x16x32_bf16 v[92:95], v[140:143], v[200:203], v[92:95]
	v_mfma_f32_16x16x32_bf16 v[80:83], v[132:135], v[208:211], v[80:83]
	v_mfma_f32_16x16x32_bf16 v[76:79], v[140:143], v[208:211], v[76:79]
	v_mfma_f32_16x16x32_bf16 v[128:131], v[136:139], v[188:191], v[128:131]
	v_mfma_f32_16x16x32_bf16 v[124:127], v[144:147], v[188:191], v[124:127]
	v_mfma_f32_16x16x32_bf16 v[112:115], v[136:139], v[196:199], v[112:115]
	v_mfma_f32_16x16x32_bf16 v[108:111], v[144:147], v[196:199], v[108:111]
	v_mfma_f32_16x16x32_bf16 v[96:99], v[136:139], v[204:207], v[96:99]
	v_mfma_f32_16x16x32_bf16 v[92:95], v[144:147], v[204:207], v[92:95]
	v_mfma_f32_16x16x32_bf16 v[80:83], v[136:139], v[212:215], v[80:83]
	v_mfma_f32_16x16x32_bf16 v[76:79], v[144:147], v[212:215], v[76:79]
	v_mfma_f32_16x16x32_bf16 v[120:123], v[148:151], v[164:167], v[120:123]
	v_mfma_f32_16x16x32_bf16 v[116:119], v[156:159], v[164:167], v[116:119]
	v_mfma_f32_16x16x32_bf16 v[104:107], v[148:151], v[192:195], v[104:107]
	v_mfma_f32_16x16x32_bf16 v[100:103], v[156:159], v[192:195], v[100:103]
	v_mfma_f32_16x16x32_bf16 v[88:91], v[148:151], v[200:203], v[88:91]
	v_mfma_f32_16x16x32_bf16 v[84:87], v[156:159], v[200:203], v[84:87]
	v_mfma_f32_16x16x32_bf16 v[72:75], v[148:151], v[208:211], v[72:75]
	v_mfma_f32_16x16x32_bf16 v[68:71], v[156:159], v[208:211], v[68:71]
	v_mfma_f32_16x16x32_bf16 v[120:123], v[152:155], v[188:191], v[120:123]
	v_mfma_f32_16x16x32_bf16 v[116:119], v[160:163], v[188:191], v[116:119]
	v_mfma_f32_16x16x32_bf16 v[104:107], v[152:155], v[196:199], v[104:107]
	v_mfma_f32_16x16x32_bf16 v[100:103], v[160:163], v[196:199], v[100:103]
	v_mfma_f32_16x16x32_bf16 v[88:91], v[152:155], v[204:207], v[88:91]
	v_mfma_f32_16x16x32_bf16 v[84:87], v[160:163], v[204:207], v[84:87]
	v_mfma_f32_16x16x32_bf16 v[72:75], v[152:155], v[212:215], v[72:75]
	v_mfma_f32_16x16x32_bf16 v[68:71], v[160:163], v[212:215], v[68:71]
	s_barrier
	s_setprio 0
	s_add_i32 s16, s16, s74
	v_lshl_add_u64 v[174:175], s[28:29], 0, v[2:3]
	s_mov_b32 m0, s16
	ds_read_b128 v[164:167], v246 offset:16384
	ds_read_b128 v[188:191], v246 offset:17408
	ds_read_b128 v[192:195], v246 offset:18432
	ds_read_b128 v[196:199], v246 offset:19456
	ds_read_b128 v[200:203], v246 offset:20480
	ds_read_b128 v[204:207], v246 offset:21504
	ds_read_b128 v[208:211], v246 offset:22528
	ds_read_b128 v[212:215], v246 offset:23552
	global_load_lds_dwordx4 v[174:175], off
	s_add_i32 m0, s16, 0x2000
	s_add_u32 s16, s28, 0x58000
	v_lshl_add_u64 v[176:177], s[28:29], 0, v[168:169]
	s_addc_u32 s17, s29, 0
	s_add_i32 s49, s49, s74
	global_load_lds_dwordx4 v[176:177], off
	v_lshl_add_u64 v[178:179], s[16:17], 0, v[2:3]
	s_mov_b32 m0, s49
	v_lshl_add_u64 v[180:181], s[72:73], 0, v[170:171]
	global_load_lds_dwordx4 v[178:179], off
	v_lshl_add_u64 v[178:179], s[16:17], 0, v[168:169]
	s_add_i32 m0, s49, 0x2000
	s_nop 0
	global_load_lds_dwordx4 v[178:179], off
	v_lshl_add_u64 v[178:179], s[72:73], 0, v[172:173]
	s_mov_b32 m0, s77
	s_nop 0
	global_load_lds_dwordx4 v[178:179], off
	s_mov_b32 m0, s78
	s_nop 0
	global_load_lds_dwordx4 v[180:181], off
	s_waitcnt vmcnt(8)
	s_waitcnt lgkmcnt(0)
	s_setprio 1
	s_barrier
	v_mfma_f32_16x16x32_bf16 v[64:67], v[132:135], v[164:167], v[64:67]
	v_mfma_f32_16x16x32_bf16 v[60:63], v[140:143], v[164:167], v[60:63]
	v_mfma_f32_16x16x32_bf16 v[48:51], v[132:135], v[192:195], v[48:51]
	v_mfma_f32_16x16x32_bf16 v[44:47], v[140:143], v[192:195], v[44:47]
	v_mfma_f32_16x16x32_bf16 v[32:35], v[132:135], v[200:203], v[32:35]
	v_mfma_f32_16x16x32_bf16 v[28:31], v[140:143], v[200:203], v[28:31]
	v_mfma_f32_16x16x32_bf16 v[16:19], v[132:135], v[208:211], v[16:19]
	v_mfma_f32_16x16x32_bf16 v[12:15], v[140:143], v[208:211], v[12:15]
	v_mfma_f32_16x16x32_bf16 v[64:67], v[136:139], v[188:191], v[64:67]
	v_mfma_f32_16x16x32_bf16 v[60:63], v[144:147], v[188:191], v[60:63]
	v_mfma_f32_16x16x32_bf16 v[48:51], v[136:139], v[196:199], v[48:51]
	v_mfma_f32_16x16x32_bf16 v[44:47], v[144:147], v[196:199], v[44:47]
	v_mfma_f32_16x16x32_bf16 v[32:35], v[136:139], v[204:207], v[32:35]
	v_mfma_f32_16x16x32_bf16 v[28:31], v[144:147], v[204:207], v[28:31]
	v_mfma_f32_16x16x32_bf16 v[16:19], v[136:139], v[212:215], v[16:19]
	v_mfma_f32_16x16x32_bf16 v[12:15], v[144:147], v[212:215], v[12:15]
	v_mfma_f32_16x16x32_bf16 v[56:59], v[148:151], v[164:167], v[56:59]
	v_mfma_f32_16x16x32_bf16 v[52:55], v[156:159], v[164:167], v[52:55]
	v_mfma_f32_16x16x32_bf16 v[40:43], v[148:151], v[192:195], v[40:43]
	v_mfma_f32_16x16x32_bf16 v[36:39], v[156:159], v[192:195], v[36:39]
	v_mfma_f32_16x16x32_bf16 v[24:27], v[148:151], v[200:203], v[24:27]
	v_mfma_f32_16x16x32_bf16 v[20:23], v[156:159], v[200:203], v[20:23]
	v_mfma_f32_16x16x32_bf16 v[8:11], v[148:151], v[208:211], v[8:11]
	v_mfma_f32_16x16x32_bf16 v[4:7], v[156:159], v[208:211], v[4:7]
	v_mfma_f32_16x16x32_bf16 v[56:59], v[152:155], v[188:191], v[56:59]
	v_mfma_f32_16x16x32_bf16 v[52:55], v[160:163], v[188:191], v[52:55]
	v_mfma_f32_16x16x32_bf16 v[40:43], v[152:155], v[196:199], v[40:43]
	v_mfma_f32_16x16x32_bf16 v[36:39], v[160:163], v[196:199], v[36:39]
	v_mfma_f32_16x16x32_bf16 v[24:27], v[152:155], v[204:207], v[24:27]
	v_mfma_f32_16x16x32_bf16 v[20:23], v[160:163], v[204:207], v[20:23]
	v_mfma_f32_16x16x32_bf16 v[8:11], v[152:155], v[212:215], v[8:11]
	v_mfma_f32_16x16x32_bf16 v[4:7], v[160:163], v[212:215], v[4:7]
	s_barrier
	s_setprio 0
	s_add_i32 s49, 0, 0x18000
	s_add_i32 s50, 0, 0x1c000
	v_add_u32_e32 v144, s49, v244
	v_add_u32_e32 v160, s50, v244
	ds_read_b128 v[132:135], v144
	ds_read_b128 v[136:139], v144 offset:1024
	ds_read_b128 v[140:143], v144 offset:2048
	ds_read_b128 v[144:147], v144 offset:3072
	ds_read_b128 v[148:151], v160
	ds_read_b128 v[152:155], v160 offset:1024
	ds_read_b128 v[156:159], v160 offset:2048
	ds_read_b128 v[160:163], v160 offset:3072
	s_add_u32 s16, s72, 0x160000
	s_addc_u32 s17, s73, 0
	s_mov_b32 m0, s18
	v_lshl_add_u64 v[182:183], s[16:17], 0, v[172:173]
	ds_read_b128 v[164:167], v246 offset:32768
	ds_read_b128 v[188:191], v246 offset:33792
	ds_read_b128 v[192:195], v246 offset:34816
	ds_read_b128 v[196:199], v246 offset:35840
	ds_read_b128 v[200:203], v246 offset:36864
	ds_read_b128 v[204:207], v246 offset:37888
	ds_read_b128 v[208:211], v246 offset:38912
	ds_read_b128 v[212:215], v246 offset:39936
	global_load_lds_dwordx4 v[182:183], off
	v_lshl_add_u64 v[182:183], s[16:17], 0, v[170:171]
	s_mov_b32 m0, s19
	s_nop 0
	global_load_lds_dwordx4 v[182:183], off
	s_waitcnt vmcnt(8)
	s_waitcnt lgkmcnt(0)
	s_setprio 1
	s_barrier
	v_mfma_f32_16x16x32_bf16 v[128:131], v[132:135], v[164:167], v[128:131]
	v_mfma_f32_16x16x32_bf16 v[124:127], v[140:143], v[164:167], v[124:127]
	v_mfma_f32_16x16x32_bf16 v[112:115], v[132:135], v[192:195], v[112:115]
	v_mfma_f32_16x16x32_bf16 v[108:111], v[140:143], v[192:195], v[108:111]
	v_mfma_f32_16x16x32_bf16 v[96:99], v[132:135], v[200:203], v[96:99]
	v_mfma_f32_16x16x32_bf16 v[92:95], v[140:143], v[200:203], v[92:95]
	v_mfma_f32_16x16x32_bf16 v[80:83], v[132:135], v[208:211], v[80:83]
	v_mfma_f32_16x16x32_bf16 v[76:79], v[140:143], v[208:211], v[76:79]
	v_mfma_f32_16x16x32_bf16 v[128:131], v[136:139], v[188:191], v[128:131]
	v_mfma_f32_16x16x32_bf16 v[124:127], v[144:147], v[188:191], v[124:127]
	v_mfma_f32_16x16x32_bf16 v[112:115], v[136:139], v[196:199], v[112:115]
	v_mfma_f32_16x16x32_bf16 v[108:111], v[144:147], v[196:199], v[108:111]
	v_mfma_f32_16x16x32_bf16 v[96:99], v[136:139], v[204:207], v[96:99]
	v_mfma_f32_16x16x32_bf16 v[92:95], v[144:147], v[204:207], v[92:95]
	v_mfma_f32_16x16x32_bf16 v[80:83], v[136:139], v[212:215], v[80:83]
	v_mfma_f32_16x16x32_bf16 v[76:79], v[144:147], v[212:215], v[76:79]
	v_mfma_f32_16x16x32_bf16 v[120:123], v[148:151], v[164:167], v[120:123]
	v_mfma_f32_16x16x32_bf16 v[116:119], v[156:159], v[164:167], v[116:119]
	v_mfma_f32_16x16x32_bf16 v[104:107], v[148:151], v[192:195], v[104:107]
	v_mfma_f32_16x16x32_bf16 v[100:103], v[156:159], v[192:195], v[100:103]
	v_mfma_f32_16x16x32_bf16 v[88:91], v[148:151], v[200:203], v[88:91]
	v_mfma_f32_16x16x32_bf16 v[84:87], v[156:159], v[200:203], v[84:87]
	v_mfma_f32_16x16x32_bf16 v[72:75], v[148:151], v[208:211], v[72:75]
	v_mfma_f32_16x16x32_bf16 v[68:71], v[156:159], v[208:211], v[68:71]
	v_mfma_f32_16x16x32_bf16 v[120:123], v[152:155], v[188:191], v[120:123]
	v_mfma_f32_16x16x32_bf16 v[116:119], v[160:163], v[188:191], v[116:119]
	v_mfma_f32_16x16x32_bf16 v[104:107], v[152:155], v[196:199], v[104:107]
	v_mfma_f32_16x16x32_bf16 v[100:103], v[160:163], v[196:199], v[100:103]
	v_mfma_f32_16x16x32_bf16 v[88:91], v[152:155], v[204:207], v[88:91]
	v_mfma_f32_16x16x32_bf16 v[84:87], v[160:163], v[204:207], v[84:87]
	v_mfma_f32_16x16x32_bf16 v[72:75], v[152:155], v[212:215], v[72:75]
	v_mfma_f32_16x16x32_bf16 v[68:71], v[160:163], v[212:215], v[68:71]
	s_barrier
	s_setprio 0
	s_add_i32 s16, s49, s74
	v_lshl_add_u64 v[174:175], v[174:175], 0, s[24:25]
	s_mov_b32 m0, s16
	ds_read_b128 v[164:167], v246 offset:49152
	ds_read_b128 v[188:191], v246 offset:50176
	ds_read_b128 v[192:195], v246 offset:51200
	ds_read_b128 v[196:199], v246 offset:52224
	ds_read_b128 v[200:203], v246 offset:53248
	ds_read_b128 v[204:207], v246 offset:54272
	ds_read_b128 v[208:211], v246 offset:55296
	ds_read_b128 v[212:215], v246 offset:56320
	global_load_lds_dwordx4 v[174:175], off
	s_add_i32 m0, s16, 0x2000
	s_add_u32 s16, s28, 0x58080
	v_lshl_add_u64 v[174:175], v[176:177], 0, s[24:25]
	s_addc_u32 s17, s29, 0
	s_add_i32 s28, s50, s74
	global_load_lds_dwordx4 v[174:175], off
	v_lshl_add_u64 v[174:175], s[16:17], 0, v[2:3]
	s_mov_b32 m0, s28
	s_nop 0
	global_load_lds_dwordx4 v[174:175], off
	v_lshl_add_u64 v[174:175], s[16:17], 0, v[168:169]
	s_add_i32 m0, s28, 0x2000
	s_nop 0
	global_load_lds_dwordx4 v[174:175], off
	v_lshl_add_u64 v[174:175], v[178:179], 0, s[24:25]
	s_mov_b32 m0, s96
	s_nop 0
	global_load_lds_dwordx4 v[174:175], off
	v_lshl_add_u64 v[174:175], v[180:181], 0, s[24:25]
	s_mov_b32 m0, s3
	s_nop 0
	global_load_lds_dwordx4 v[174:175], off
	s_waitcnt vmcnt(8)
	s_waitcnt lgkmcnt(0)
	s_setprio 1
	s_barrier
	v_mfma_f32_16x16x32_bf16 v[64:67], v[132:135], v[164:167], v[64:67]
	v_mfma_f32_16x16x32_bf16 v[60:63], v[140:143], v[164:167], v[60:63]
	v_mfma_f32_16x16x32_bf16 v[48:51], v[132:135], v[192:195], v[48:51]
	v_mfma_f32_16x16x32_bf16 v[44:47], v[140:143], v[192:195], v[44:47]
	v_mfma_f32_16x16x32_bf16 v[32:35], v[132:135], v[200:203], v[32:35]
	v_mfma_f32_16x16x32_bf16 v[28:31], v[140:143], v[200:203], v[28:31]
	v_mfma_f32_16x16x32_bf16 v[16:19], v[132:135], v[208:211], v[16:19]
	v_mfma_f32_16x16x32_bf16 v[12:15], v[140:143], v[208:211], v[12:15]
	v_mfma_f32_16x16x32_bf16 v[64:67], v[136:139], v[188:191], v[64:67]
	v_mfma_f32_16x16x32_bf16 v[60:63], v[144:147], v[188:191], v[60:63]
	v_mfma_f32_16x16x32_bf16 v[48:51], v[136:139], v[196:199], v[48:51]
	v_mfma_f32_16x16x32_bf16 v[44:47], v[144:147], v[196:199], v[44:47]
	v_mfma_f32_16x16x32_bf16 v[32:35], v[136:139], v[204:207], v[32:35]
	v_mfma_f32_16x16x32_bf16 v[28:31], v[144:147], v[204:207], v[28:31]
	v_mfma_f32_16x16x32_bf16 v[16:19], v[136:139], v[212:215], v[16:19]
	v_mfma_f32_16x16x32_bf16 v[12:15], v[144:147], v[212:215], v[12:15]
	v_mfma_f32_16x16x32_bf16 v[56:59], v[148:151], v[164:167], v[56:59]
	v_mfma_f32_16x16x32_bf16 v[52:55], v[156:159], v[164:167], v[52:55]
	v_mfma_f32_16x16x32_bf16 v[40:43], v[148:151], v[192:195], v[40:43]
	v_mfma_f32_16x16x32_bf16 v[36:39], v[156:159], v[192:195], v[36:39]
	v_mfma_f32_16x16x32_bf16 v[24:27], v[148:151], v[200:203], v[24:27]
	v_mfma_f32_16x16x32_bf16 v[20:23], v[156:159], v[200:203], v[20:23]
	v_mfma_f32_16x16x32_bf16 v[8:11], v[148:151], v[208:211], v[8:11]
	v_mfma_f32_16x16x32_bf16 v[4:7], v[156:159], v[208:211], v[4:7]
	v_mfma_f32_16x16x32_bf16 v[56:59], v[152:155], v[188:191], v[56:59]
	v_mfma_f32_16x16x32_bf16 v[52:55], v[160:163], v[188:191], v[52:55]
	v_mfma_f32_16x16x32_bf16 v[40:43], v[152:155], v[196:199], v[40:43]
	v_mfma_f32_16x16x32_bf16 v[36:39], v[160:163], v[196:199], v[36:39]
	v_mfma_f32_16x16x32_bf16 v[24:27], v[152:155], v[204:207], v[24:27]
	v_mfma_f32_16x16x32_bf16 v[20:23], v[160:163], v[204:207], v[20:23]
	v_mfma_f32_16x16x32_bf16 v[8:11], v[152:155], v[212:215], v[8:11]
	v_mfma_f32_16x16x32_bf16 v[4:7], v[160:163], v[212:215], v[4:7]
	s_barrier
	s_setprio 0
	s_add_i32 s48, s48, 2
	s_add_u32 vcc_lo, vcc_lo, 0x100
	s_addc_u32 vcc_hi, vcc_hi, 0
	s_cmpk_gt_u32 s48, 0x55
	s_mov_b64 s[50:51], s[46:47]
	s_cbranch_scc0 .LBB0_1035
	v_readlane_b32 s16, v252, 12
	v_readlane_b32 s17, v252, 13
	s_and_b64 vcc, exec, s[16:17]
	s_cbranch_vccz .LBB0_1038
	s_barrier
